# GEMM K-loops: per-segment s_setprio toggles removed; waves 4-7 (trailing half) run each K-loop at static s_setprio 1; otherwise as v71
# baseline (speedup 1.0000x reference)
.LBB0_319:
	s_ashr_i32 s49, s48, 31
	s_lshl_b64 s[50:51], s[48:49], 19
	s_add_u32 s50, s63, s50
	s_addc_u32 s51, s64, s51
	s_and_b64 s[52:53], s[38:39], exec
	s_cselect_b32 s49, s51, s21
	s_cselect_b32 s55, s50, s20
	s_ashr_i32 s45, s44, 31
	s_lshl_b64 s[52:53], s[44:45], 19
	s_add_u32 s52, s61, s52
	s_addc_u32 s53, s60, s53
	s_and_b64 s[58:59], s[38:39], exec
	s_cselect_b32 s45, s53, s41
	s_cselect_b32 s73, s52, s40
	s_add_u32 s74, s40, 0x100
	s_addc_u32 s75, s41, 0
	s_add_u32 s40, s20, 0x40080
	v_mov_b32_e32 v0, 0
	s_addc_u32 s41, s21, 0
	s_mov_b32 s76, -2
	v_mov_b32_e32 v1, v0
	v_mov_b32_e32 v2, v0
	v_mov_b32_e32 v3, v0
	v_mov_b32_e32 v4, v0
	v_mov_b32_e32 v5, v0
	v_mov_b32_e32 v6, v0
	v_mov_b32_e32 v7, v0
	v_mov_b32_e32 v16, v0
	v_mov_b32_e32 v17, v0
	v_mov_b32_e32 v18, v0
	v_mov_b32_e32 v19, v0
	v_mov_b32_e32 v20, v0
	v_mov_b32_e32 v21, v0
	v_mov_b32_e32 v22, v0
	v_mov_b32_e32 v23, v0
	v_mov_b32_e32 v32, v0
	v_mov_b32_e32 v33, v0
	v_mov_b32_e32 v34, v0
	v_mov_b32_e32 v35, v0
	v_mov_b32_e32 v36, v0
	v_mov_b32_e32 v37, v0
	v_mov_b32_e32 v38, v0
	v_mov_b32_e32 v39, v0
	v_mov_b32_e32 v64, v0
	v_mov_b32_e32 v65, v0
	v_mov_b32_e32 v66, v0
	v_mov_b32_e32 v67, v0
	v_mov_b32_e32 v68, v0
	v_mov_b32_e32 v69, v0
	v_mov_b32_e32 v70, v0
	v_mov_b32_e32 v71, v0
	v_mov_b32_e32 v8, v0
	v_mov_b32_e32 v9, v0
	v_mov_b32_e32 v10, v0
	v_mov_b32_e32 v11, v0
	v_mov_b32_e32 v12, v0
	v_mov_b32_e32 v13, v0
	v_mov_b32_e32 v14, v0
	v_mov_b32_e32 v15, v0
	v_mov_b32_e32 v24, v0
	v_mov_b32_e32 v25, v0
	v_mov_b32_e32 v26, v0
	v_mov_b32_e32 v27, v0
	v_mov_b32_e32 v28, v0
	v_mov_b32_e32 v29, v0
	v_mov_b32_e32 v30, v0
	v_mov_b32_e32 v31, v0
	v_mov_b32_e32 v40, v0
	v_mov_b32_e32 v41, v0
	v_mov_b32_e32 v42, v0
	v_mov_b32_e32 v43, v0
	v_mov_b32_e32 v44, v0
	v_mov_b32_e32 v45, v0
	v_mov_b32_e32 v46, v0
	v_mov_b32_e32 v47, v0
	v_mov_b32_e32 v72, v0
	v_mov_b32_e32 v73, v0
	v_mov_b32_e32 v74, v0
	v_mov_b32_e32 v75, v0
	v_mov_b32_e32 v76, v0
	v_mov_b32_e32 v77, v0
	v_mov_b32_e32 v78, v0
	v_mov_b32_e32 v79, v0
	v_mov_b32_e32 v80, v0
	v_mov_b32_e32 v81, v0
	v_mov_b32_e32 v82, v0
	v_mov_b32_e32 v83, v0
	v_mov_b32_e32 v84, v0
	v_mov_b32_e32 v85, v0
	v_mov_b32_e32 v86, v0
	v_mov_b32_e32 v87, v0
	v_mov_b32_e32 v96, v0
	v_mov_b32_e32 v97, v0
	v_mov_b32_e32 v98, v0
	v_mov_b32_e32 v99, v0
	v_mov_b32_e32 v100, v0
	v_mov_b32_e32 v101, v0
	v_mov_b32_e32 v102, v0
	v_mov_b32_e32 v103, v0
	v_mov_b32_e32 v112, v0
	v_mov_b32_e32 v113, v0
	v_mov_b32_e32 v114, v0
	v_mov_b32_e32 v115, v0
	v_mov_b32_e32 v116, v0
	v_mov_b32_e32 v117, v0
	v_mov_b32_e32 v118, v0
	v_mov_b32_e32 v119, v0
	v_mov_b32_e32 v128, v0
	v_mov_b32_e32 v129, v0
	v_mov_b32_e32 v130, v0
	v_mov_b32_e32 v131, v0
	v_mov_b32_e32 v132, v0
	v_mov_b32_e32 v133, v0
	v_mov_b32_e32 v134, v0
	v_mov_b32_e32 v135, v0
	v_mov_b32_e32 v88, v0
	v_mov_b32_e32 v89, v0
	v_mov_b32_e32 v90, v0
	v_mov_b32_e32 v91, v0
	v_mov_b32_e32 v92, v0
	v_mov_b32_e32 v93, v0
	v_mov_b32_e32 v94, v0
	v_mov_b32_e32 v95, v0
	v_mov_b32_e32 v104, v0
	v_mov_b32_e32 v105, v0
	v_mov_b32_e32 v106, v0
	v_mov_b32_e32 v107, v0
	v_mov_b32_e32 v108, v0
	v_mov_b32_e32 v109, v0
	v_mov_b32_e32 v110, v0
	v_mov_b32_e32 v111, v0
	v_mov_b32_e32 v120, v0
	v_mov_b32_e32 v121, v0
	v_mov_b32_e32 v122, v0
	v_mov_b32_e32 v123, v0
	v_mov_b32_e32 v124, v0
	v_mov_b32_e32 v125, v0
	v_mov_b32_e32 v126, v0
	v_mov_b32_e32 v127, v0
	v_mov_b32_e32 v136, v0
	v_mov_b32_e32 v137, v0
	v_mov_b32_e32 v138, v0
	v_mov_b32_e32 v139, v0
	v_mov_b32_e32 v140, v0
	v_mov_b32_e32 v141, v0
	v_mov_b32_e32 v142, v0
	v_mov_b32_e32 v143, v0
	s_cmpk_lt_u32 s81, 0x100
	s_cbranch_scc1 .Lgprio_KV
	s_setprio 1
.Lgprio_KV:
.LBB0_320:
	s_add_u32 s20, s40, 0xfffc0080
	s_addc_u32 s21, s41, -1
	s_add_i32 s77, 0, 0x10000
	s_cmp_eq_u32 s76, 12
	s_cselect_b32 s59, s49, s21
	s_cselect_b32 s58, s55, s20
	s_cselect_b32 s21, s45, s75
	s_cselect_b32 s20, s73, s74
	s_add_i32 s80, 0, 0x14000
	v_add_u32_e32 v60, s77, v183
	v_add_u32_e32 v168, s80, v183
	ds_read_b128 v[48:51], v60
	ds_read_b128 v[52:55], v60 offset:1024
	ds_read_b128 v[56:59], v60 offset:2048
	ds_read_b128 v[60:63], v60 offset:3072
	ds_read_b128 v[164:167], v168
	ds_read_b128 v[170:173], v168 offset:1024
	ds_read_b128 v[174:177], v168 offset:2048
	ds_read_b128 v[178:181], v168 offset:3072
	v_lshl_add_u64 v[228:229], s[40:41], 0, v[162:163]
	s_add_i32 m0, s57, 0xc000
	ds_read_b128 v[204:207], v202
	ds_read_b128 v[208:211], v202 offset:1024
	ds_read_b128 v[212:215], v202 offset:2048
	ds_read_b128 v[216:219], v202 offset:3072
	ds_read_b128 v[220:223], v202 offset:4096
	ds_read_b128 v[224:227], v202 offset:5120
	ds_read_b128 v[240:243], v202 offset:6144
	ds_read_b128 v[244:247], v202 offset:7168
	global_load_lds_dwordx4 v[228:229], off
	v_lshl_add_u64 v[228:229], s[40:41], 0, v[160:161]
	s_add_i32 m0, s57, 0xe000
	s_nop 0
	global_load_lds_dwordx4 v[228:229], off
	s_waitcnt vmcnt(8)
	s_waitcnt lgkmcnt(0)
	s_barrier
	v_mfma_f32_16x16x32_bf16 v[140:143], v[48:51], v[204:207], v[140:143]
	v_mfma_f32_16x16x32_bf16 v[140:143], v[52:55], v[208:211], v[140:143]
	v_mfma_f32_16x16x32_bf16 v[136:139], v[56:59], v[204:207], v[136:139]
	v_mfma_f32_16x16x32_bf16 v[136:139], v[60:63], v[208:211], v[136:139]
	v_mfma_f32_16x16x32_bf16 v[124:127], v[48:51], v[212:215], v[124:127]
	v_mfma_f32_16x16x32_bf16 v[124:127], v[52:55], v[216:219], v[124:127]
	v_mfma_f32_16x16x32_bf16 v[120:123], v[56:59], v[212:215], v[120:123]
	v_mfma_f32_16x16x32_bf16 v[120:123], v[60:63], v[216:219], v[120:123]
	v_mfma_f32_16x16x32_bf16 v[108:111], v[48:51], v[220:223], v[108:111]
	v_mfma_f32_16x16x32_bf16 v[108:111], v[52:55], v[224:227], v[108:111]
	v_mfma_f32_16x16x32_bf16 v[104:107], v[56:59], v[220:223], v[104:107]
	v_mfma_f32_16x16x32_bf16 v[104:107], v[60:63], v[224:227], v[104:107]
	v_mfma_f32_16x16x32_bf16 v[92:95], v[48:51], v[240:243], v[92:95]
	v_mfma_f32_16x16x32_bf16 v[92:95], v[52:55], v[244:247], v[92:95]
	v_mfma_f32_16x16x32_bf16 v[88:91], v[56:59], v[240:243], v[88:91]
	v_mfma_f32_16x16x32_bf16 v[88:91], v[60:63], v[244:247], v[88:91]
	v_mfma_f32_16x16x32_bf16 v[132:135], v[164:167], v[204:207], v[132:135]
	v_mfma_f32_16x16x32_bf16 v[132:135], v[170:173], v[208:211], v[132:135]
	v_mfma_f32_16x16x32_bf16 v[128:131], v[174:177], v[204:207], v[128:131]
	v_mfma_f32_16x16x32_bf16 v[128:131], v[178:181], v[208:211], v[128:131]
	v_mfma_f32_16x16x32_bf16 v[116:119], v[164:167], v[212:215], v[116:119]
	v_mfma_f32_16x16x32_bf16 v[116:119], v[170:173], v[216:219], v[116:119]
	v_mfma_f32_16x16x32_bf16 v[112:115], v[174:177], v[212:215], v[112:115]
	v_mfma_f32_16x16x32_bf16 v[112:115], v[178:181], v[216:219], v[112:115]
	v_mfma_f32_16x16x32_bf16 v[100:103], v[164:167], v[220:223], v[100:103]
	v_mfma_f32_16x16x32_bf16 v[100:103], v[170:173], v[224:227], v[100:103]
	v_mfma_f32_16x16x32_bf16 v[96:99], v[174:177], v[220:223], v[96:99]
	v_mfma_f32_16x16x32_bf16 v[96:99], v[178:181], v[224:227], v[96:99]
	v_mfma_f32_16x16x32_bf16 v[84:87], v[164:167], v[240:243], v[84:87]
	v_mfma_f32_16x16x32_bf16 v[84:87], v[170:173], v[244:247], v[84:87]
	v_mfma_f32_16x16x32_bf16 v[80:83], v[174:177], v[240:243], v[80:83]
	v_mfma_f32_16x16x32_bf16 v[80:83], v[178:181], v[244:247], v[80:83]
	s_barrier
	s_add_i32 s77, s77, s62
	v_lshl_add_u64 v[228:229], s[20:21], 0, v[146:147]
	s_mov_b32 m0, s77
	ds_read_b128 v[204:207], v202 offset:16384
	ds_read_b128 v[208:211], v202 offset:17408
	ds_read_b128 v[212:215], v202 offset:18432
	ds_read_b128 v[216:219], v202 offset:19456
	ds_read_b128 v[220:223], v202 offset:20480
	ds_read_b128 v[224:227], v202 offset:21504
	ds_read_b128 v[240:243], v202 offset:22528
	ds_read_b128 v[244:247], v202 offset:23552
	global_load_lds_dwordx4 v[228:229], off
	s_add_i32 m0, s77, 0x2000
	s_add_u32 s78, s20, 0x40000
	v_lshl_add_u64 v[230:231], s[20:21], 0, v[150:151]
	s_addc_u32 s79, s21, 0
	s_add_i32 s77, s80, s62
	global_load_lds_dwordx4 v[230:231], off
	v_lshl_add_u64 v[232:233], s[78:79], 0, v[146:147]
	s_mov_b32 m0, s77
	v_lshl_add_u64 v[234:235], s[58:59], 0, v[148:149]
	global_load_lds_dwordx4 v[232:233], off
	v_lshl_add_u64 v[232:233], s[78:79], 0, v[150:151]
	s_add_i32 m0, s77, 0x2000
	s_nop 0
	global_load_lds_dwordx4 v[232:233], off
	v_lshl_add_u64 v[232:233], s[58:59], 0, v[144:145]
	s_mov_b32 m0, s57
	s_nop 0
	global_load_lds_dwordx4 v[232:233], off
	s_mov_b32 m0, s65
	s_nop 0
	global_load_lds_dwordx4 v[234:235], off
	s_waitcnt vmcnt(8)
	s_waitcnt lgkmcnt(0)
	s_barrier
	v_mfma_f32_16x16x32_bf16 v[76:79], v[48:51], v[204:207], v[76:79]
	v_mfma_f32_16x16x32_bf16 v[76:79], v[52:55], v[208:211], v[76:79]
	v_mfma_f32_16x16x32_bf16 v[72:75], v[56:59], v[204:207], v[72:75]
	v_mfma_f32_16x16x32_bf16 v[72:75], v[60:63], v[208:211], v[72:75]
	v_mfma_f32_16x16x32_bf16 v[44:47], v[48:51], v[212:215], v[44:47]
	v_mfma_f32_16x16x32_bf16 v[44:47], v[52:55], v[216:219], v[44:47]
	v_mfma_f32_16x16x32_bf16 v[40:43], v[56:59], v[212:215], v[40:43]
	v_mfma_f32_16x16x32_bf16 v[40:43], v[60:63], v[216:219], v[40:43]
	v_mfma_f32_16x16x32_bf16 v[28:31], v[48:51], v[220:223], v[28:31]
	v_mfma_f32_16x16x32_bf16 v[28:31], v[52:55], v[224:227], v[28:31]
	v_mfma_f32_16x16x32_bf16 v[24:27], v[56:59], v[220:223], v[24:27]
	v_mfma_f32_16x16x32_bf16 v[24:27], v[60:63], v[224:227], v[24:27]
	v_mfma_f32_16x16x32_bf16 v[12:15], v[48:51], v[240:243], v[12:15]
	v_mfma_f32_16x16x32_bf16 v[12:15], v[52:55], v[244:247], v[12:15]
	v_mfma_f32_16x16x32_bf16 v[8:11], v[56:59], v[240:243], v[8:11]
	v_mfma_f32_16x16x32_bf16 v[8:11], v[60:63], v[244:247], v[8:11]
	v_mfma_f32_16x16x32_bf16 v[36:39], v[164:167], v[212:215], v[36:39]
	v_mfma_f32_16x16x32_bf16 v[36:39], v[170:173], v[216:219], v[36:39]
	v_mfma_f32_16x16x32_bf16 v[32:35], v[174:177], v[212:215], v[32:35]
	v_mfma_f32_16x16x32_bf16 v[32:35], v[178:181], v[216:219], v[32:35]
	v_mfma_f32_16x16x32_bf16 v[20:23], v[164:167], v[220:223], v[20:23]
	v_mfma_f32_16x16x32_bf16 v[20:23], v[170:173], v[224:227], v[20:23]
	v_mfma_f32_16x16x32_bf16 v[16:19], v[174:177], v[220:223], v[16:19]
	v_mfma_f32_16x16x32_bf16 v[16:19], v[178:181], v[224:227], v[16:19]
	v_mfma_f32_16x16x32_bf16 v[4:7], v[164:167], v[240:243], v[4:7]
	v_mfma_f32_16x16x32_bf16 v[4:7], v[170:173], v[244:247], v[4:7]
	v_mfma_f32_16x16x32_bf16 v[0:3], v[174:177], v[240:243], v[0:3]
	v_mfma_f32_16x16x32_bf16 v[0:3], v[178:181], v[244:247], v[0:3]
	v_mfma_f32_16x16x32_bf16 v[48:51], v[164:167], v[204:207], v[68:71]
	v_mfma_f32_16x16x32_bf16 v[48:51], v[170:173], v[208:211], v[48:51]
	v_mfma_f32_16x16x32_bf16 v[52:55], v[174:177], v[204:207], v[64:67]
	v_mfma_f32_16x16x32_bf16 v[52:55], v[178:181], v[208:211], v[52:55]
	s_barrier
	s_add_i32 s77, 0, 0x18000
	s_add_i32 s78, 0, 0x1c000
	v_add_u32_e32 v68, s77, v183
	v_add_u32_e32 v168, s78, v183
	ds_read_b128 v[56:59], v68
	ds_read_b128 v[60:63], v68 offset:1024
	ds_read_b128 v[64:67], v68 offset:2048
	ds_read_b128 v[68:71], v68 offset:3072
	ds_read_b128 v[164:167], v168
	ds_read_b128 v[170:173], v168 offset:1024
	ds_read_b128 v[174:177], v168 offset:2048
	ds_read_b128 v[178:181], v168 offset:3072
	s_add_u32 s58, s58, 0x40000
	s_addc_u32 s59, s59, 0
	s_mov_b32 m0, s66
	v_lshl_add_u64 v[236:237], s[58:59], 0, v[144:145]
	ds_read_b128 v[204:207], v202 offset:32768
	ds_read_b128 v[208:211], v202 offset:33792
	ds_read_b128 v[212:215], v202 offset:34816
	ds_read_b128 v[216:219], v202 offset:35840
	ds_read_b128 v[220:223], v202 offset:36864
	ds_read_b128 v[224:227], v202 offset:37888
	ds_read_b128 v[240:243], v202 offset:38912
	ds_read_b128 v[244:247], v202 offset:39936
	global_load_lds_dwordx4 v[236:237], off
	v_lshl_add_u64 v[236:237], s[58:59], 0, v[148:149]
	s_mov_b32 m0, s67
	s_nop 0
	global_load_lds_dwordx4 v[236:237], off
	s_waitcnt vmcnt(8)
	s_waitcnt lgkmcnt(0)
	s_barrier
	v_mfma_f32_16x16x32_bf16 v[140:143], v[56:59], v[204:207], v[140:143]
	v_mfma_f32_16x16x32_bf16 v[140:143], v[60:63], v[208:211], v[140:143]
	v_mfma_f32_16x16x32_bf16 v[136:139], v[64:67], v[204:207], v[136:139]
	v_mfma_f32_16x16x32_bf16 v[136:139], v[68:71], v[208:211], v[136:139]
	v_mfma_f32_16x16x32_bf16 v[124:127], v[56:59], v[212:215], v[124:127]
	v_mfma_f32_16x16x32_bf16 v[124:127], v[60:63], v[216:219], v[124:127]
	v_mfma_f32_16x16x32_bf16 v[120:123], v[64:67], v[212:215], v[120:123]
	v_mfma_f32_16x16x32_bf16 v[120:123], v[68:71], v[216:219], v[120:123]
	v_mfma_f32_16x16x32_bf16 v[108:111], v[56:59], v[220:223], v[108:111]
	v_mfma_f32_16x16x32_bf16 v[108:111], v[60:63], v[224:227], v[108:111]
	v_mfma_f32_16x16x32_bf16 v[104:107], v[64:67], v[220:223], v[104:107]
	v_mfma_f32_16x16x32_bf16 v[104:107], v[68:71], v[224:227], v[104:107]
	v_mfma_f32_16x16x32_bf16 v[92:95], v[56:59], v[240:243], v[92:95]
	v_mfma_f32_16x16x32_bf16 v[92:95], v[60:63], v[244:247], v[92:95]
	v_mfma_f32_16x16x32_bf16 v[88:91], v[64:67], v[240:243], v[88:91]
	v_mfma_f32_16x16x32_bf16 v[88:91], v[68:71], v[244:247], v[88:91]
	v_mfma_f32_16x16x32_bf16 v[132:135], v[164:167], v[204:207], v[132:135]
	v_mfma_f32_16x16x32_bf16 v[132:135], v[170:173], v[208:211], v[132:135]
	v_mfma_f32_16x16x32_bf16 v[128:131], v[174:177], v[204:207], v[128:131]
	v_mfma_f32_16x16x32_bf16 v[128:131], v[178:181], v[208:211], v[128:131]
	v_mfma_f32_16x16x32_bf16 v[116:119], v[164:167], v[212:215], v[116:119]
	v_mfma_f32_16x16x32_bf16 v[116:119], v[170:173], v[216:219], v[116:119]
	v_mfma_f32_16x16x32_bf16 v[112:115], v[174:177], v[212:215], v[112:115]
	v_mfma_f32_16x16x32_bf16 v[112:115], v[178:181], v[216:219], v[112:115]
	v_mfma_f32_16x16x32_bf16 v[100:103], v[164:167], v[220:223], v[100:103]
	v_mfma_f32_16x16x32_bf16 v[100:103], v[170:173], v[224:227], v[100:103]
	v_mfma_f32_16x16x32_bf16 v[96:99], v[174:177], v[220:223], v[96:99]
	v_mfma_f32_16x16x32_bf16 v[96:99], v[178:181], v[224:227], v[96:99]
	v_mfma_f32_16x16x32_bf16 v[84:87], v[164:167], v[240:243], v[84:87]
	v_mfma_f32_16x16x32_bf16 v[84:87], v[170:173], v[244:247], v[84:87]
	v_mfma_f32_16x16x32_bf16 v[80:83], v[174:177], v[240:243], v[80:83]
	v_mfma_f32_16x16x32_bf16 v[80:83], v[178:181], v[244:247], v[80:83]
	s_barrier
	s_add_i32 s58, s77, s62
	v_lshl_add_u64 v[228:229], v[228:229], 0, s[36:37]
	s_mov_b32 m0, s58
	ds_read_b128 v[204:207], v202 offset:49152
	ds_read_b128 v[208:211], v202 offset:50176
	ds_read_b128 v[212:215], v202 offset:51200
	ds_read_b128 v[216:219], v202 offset:52224
	ds_read_b128 v[220:223], v202 offset:53248
	ds_read_b128 v[224:227], v202 offset:54272
	ds_read_b128 v[240:243], v202 offset:55296
	ds_read_b128 v[244:247], v202 offset:56320
	global_load_lds_dwordx4 v[228:229], off
	s_add_i32 m0, s58, 0x2000
	s_add_u32 s20, s20, 0x40080
	v_lshl_add_u64 v[228:229], v[230:231], 0, s[36:37]
	s_addc_u32 s21, s21, 0
	s_add_i32 s58, s78, s62
	global_load_lds_dwordx4 v[228:229], off
	v_lshl_add_u64 v[228:229], s[20:21], 0, v[146:147]
	s_mov_b32 m0, s58
	s_nop 0
	global_load_lds_dwordx4 v[228:229], off
	v_lshl_add_u64 v[228:229], s[20:21], 0, v[150:151]
	s_add_i32 m0, s58, 0x2000
	s_nop 0
	global_load_lds_dwordx4 v[228:229], off
	v_lshl_add_u64 v[228:229], v[232:233], 0, s[36:37]
	s_mov_b32 m0, s69
	s_nop 0
	global_load_lds_dwordx4 v[228:229], off
	v_lshl_add_u64 v[228:229], v[234:235], 0, s[36:37]
	s_mov_b32 m0, s70
	s_nop 0
	global_load_lds_dwordx4 v[228:229], off
	s_waitcnt vmcnt(8)
	s_waitcnt lgkmcnt(0)
	s_barrier
	v_mfma_f32_16x16x32_bf16 v[76:79], v[56:59], v[204:207], v[76:79]
	v_mfma_f32_16x16x32_bf16 v[76:79], v[60:63], v[208:211], v[76:79]
	v_mfma_f32_16x16x32_bf16 v[72:75], v[64:67], v[204:207], v[72:75]
	v_mfma_f32_16x16x32_bf16 v[72:75], v[68:71], v[208:211], v[72:75]
	v_mfma_f32_16x16x32_bf16 v[44:47], v[56:59], v[212:215], v[44:47]
	v_mfma_f32_16x16x32_bf16 v[44:47], v[60:63], v[216:219], v[44:47]
	v_mfma_f32_16x16x32_bf16 v[40:43], v[64:67], v[212:215], v[40:43]
	v_mfma_f32_16x16x32_bf16 v[40:43], v[68:71], v[216:219], v[40:43]
	v_mfma_f32_16x16x32_bf16 v[28:31], v[56:59], v[220:223], v[28:31]
	v_mfma_f32_16x16x32_bf16 v[28:31], v[60:63], v[224:227], v[28:31]
	v_mfma_f32_16x16x32_bf16 v[24:27], v[64:67], v[220:223], v[24:27]
	v_mfma_f32_16x16x32_bf16 v[24:27], v[68:71], v[224:227], v[24:27]
	v_mfma_f32_16x16x32_bf16 v[12:15], v[56:59], v[240:243], v[12:15]
	v_mfma_f32_16x16x32_bf16 v[12:15], v[60:63], v[244:247], v[12:15]
	v_mfma_f32_16x16x32_bf16 v[8:11], v[64:67], v[240:243], v[8:11]
	v_mfma_f32_16x16x32_bf16 v[8:11], v[68:71], v[244:247], v[8:11]
	v_mfma_f32_16x16x32_bf16 v[48:51], v[164:167], v[204:207], v[48:51]
	v_mfma_f32_16x16x32_bf16 v[68:71], v[170:173], v[208:211], v[48:51]
	v_mfma_f32_16x16x32_bf16 v[48:51], v[174:177], v[204:207], v[52:55]
	v_mfma_f32_16x16x32_bf16 v[36:39], v[164:167], v[212:215], v[36:39]
	v_mfma_f32_16x16x32_bf16 v[32:35], v[174:177], v[212:215], v[32:35]
	v_mfma_f32_16x16x32_bf16 v[20:23], v[164:167], v[220:223], v[20:23]
	v_mfma_f32_16x16x32_bf16 v[16:19], v[174:177], v[220:223], v[16:19]
	v_mfma_f32_16x16x32_bf16 v[4:7], v[164:167], v[240:243], v[4:7]
	v_mfma_f32_16x16x32_bf16 v[0:3], v[174:177], v[240:243], v[0:3]
	v_mfma_f32_16x16x32_bf16 v[64:67], v[178:181], v[208:211], v[48:51]
	v_mfma_f32_16x16x32_bf16 v[36:39], v[170:173], v[216:219], v[36:39]
	v_mfma_f32_16x16x32_bf16 v[32:35], v[178:181], v[216:219], v[32:35]
	v_mfma_f32_16x16x32_bf16 v[20:23], v[170:173], v[224:227], v[20:23]
	v_mfma_f32_16x16x32_bf16 v[16:19], v[178:181], v[224:227], v[16:19]
	v_mfma_f32_16x16x32_bf16 v[4:7], v[170:173], v[244:247], v[4:7]
	v_mfma_f32_16x16x32_bf16 v[0:3], v[178:181], v[244:247], v[0:3]
	s_barrier
	s_add_i32 s76, s76, 2
	s_add_u32 s74, s74, 0x100
	s_addc_u32 s75, s75, 0
	s_add_u32 s40, s40, 0x100
	s_addc_u32 s41, s41, 0
	s_cmp_gt_u32 s76, 13
	s_cbranch_scc0 .LBB0_320
	s_setprio 0
	s_and_b64 vcc, exec, s[42:43]
	s_cbranch_vccz .LBB0_323
	s_barrier

.LBB0_477:
	s_ashr_i32 s15, s14, 31
	s_lshl_b64 s[16:17], s[14:15], 19
	s_add_u32 s16, s51, s16
	s_addc_u32 s17, s52, s17
	s_and_b64 s[18:19], s[38:39], exec
	s_cselect_b32 s15, s17, s21
	s_cselect_b32 s45, s16, s20
	s_ashr_i32 s13, s12, 31
	s_lshl_b64 s[18:19], s[12:13], 19
	s_add_u32 s18, s48, s18
	s_addc_u32 s19, s49, s19
	s_and_b64 s[42:43], s[38:39], exec
	s_cselect_b32 s13, s19, s41
	s_cselect_b32 s61, s18, s40
	s_add_u32 s62, s40, 0x100
	s_addc_u32 s63, s41, 0
	s_add_u32 s40, s20, 0x40080
	v_mov_b32_e32 v0, 0
	v_mov_b32_e32 v168, 0x358637bd
	s_addc_u32 s41, s21, 0
	s_mov_b32 s64, -2
	v_mov_b32_e32 v1, v0
	v_mov_b32_e32 v2, v0
	v_mov_b32_e32 v3, v0
	v_mov_b32_e32 v4, v0
	v_mov_b32_e32 v5, v0
	v_mov_b32_e32 v6, v0
	v_mov_b32_e32 v7, v0
	v_mov_b32_e32 v16, v0
	v_mov_b32_e32 v17, v0
	v_mov_b32_e32 v18, v0
	v_mov_b32_e32 v19, v0
	v_mov_b32_e32 v20, v0
	v_mov_b32_e32 v21, v0
	v_mov_b32_e32 v22, v0
	v_mov_b32_e32 v23, v0
	v_mov_b32_e32 v32, v0
	v_mov_b32_e32 v33, v0
	v_mov_b32_e32 v34, v0
	v_mov_b32_e32 v35, v0
	v_mov_b32_e32 v36, v0
	v_mov_b32_e32 v37, v0
	v_mov_b32_e32 v38, v0
	v_mov_b32_e32 v39, v0
	v_mov_b32_e32 v48, v0
	v_mov_b32_e32 v49, v0
	v_mov_b32_e32 v50, v0
	v_mov_b32_e32 v51, v0
	v_mov_b32_e32 v52, v0
	v_mov_b32_e32 v53, v0
	v_mov_b32_e32 v54, v0
	v_mov_b32_e32 v55, v0
	v_mov_b32_e32 v8, v0
	v_mov_b32_e32 v9, v0
	v_mov_b32_e32 v10, v0
	v_mov_b32_e32 v11, v0
	v_mov_b32_e32 v12, v0
	v_mov_b32_e32 v13, v0
	v_mov_b32_e32 v14, v0
	v_mov_b32_e32 v15, v0
	v_mov_b32_e32 v24, v0
	v_mov_b32_e32 v25, v0
	v_mov_b32_e32 v26, v0
	v_mov_b32_e32 v27, v0
	v_mov_b32_e32 v28, v0
	v_mov_b32_e32 v29, v0
	v_mov_b32_e32 v30, v0
	v_mov_b32_e32 v31, v0
	v_mov_b32_e32 v40, v0
	v_mov_b32_e32 v41, v0
	v_mov_b32_e32 v42, v0
	v_mov_b32_e32 v43, v0
	v_mov_b32_e32 v44, v0
	v_mov_b32_e32 v45, v0
	v_mov_b32_e32 v46, v0
	v_mov_b32_e32 v47, v0
	v_mov_b32_e32 v56, v0
	v_mov_b32_e32 v57, v0
	v_mov_b32_e32 v58, v0
	v_mov_b32_e32 v59, v0
	v_mov_b32_e32 v60, v0
	v_mov_b32_e32 v61, v0
	v_mov_b32_e32 v62, v0
	v_mov_b32_e32 v63, v0
	v_mov_b32_e32 v64, v0
	v_mov_b32_e32 v65, v0
	v_mov_b32_e32 v66, v0
	v_mov_b32_e32 v67, v0
	v_mov_b32_e32 v68, v0
	v_mov_b32_e32 v69, v0
	v_mov_b32_e32 v70, v0
	v_mov_b32_e32 v71, v0
	v_mov_b32_e32 v80, v0
	v_mov_b32_e32 v81, v0
	v_mov_b32_e32 v82, v0
	v_mov_b32_e32 v83, v0
	v_mov_b32_e32 v84, v0
	v_mov_b32_e32 v85, v0
	v_mov_b32_e32 v86, v0
	v_mov_b32_e32 v87, v0
	v_mov_b32_e32 v96, v0
	v_mov_b32_e32 v97, v0
	v_mov_b32_e32 v98, v0
	v_mov_b32_e32 v99, v0
	v_mov_b32_e32 v100, v0
	v_mov_b32_e32 v101, v0
	v_mov_b32_e32 v102, v0
	v_mov_b32_e32 v103, v0
	v_mov_b32_e32 v112, v0
	v_mov_b32_e32 v113, v0
	v_mov_b32_e32 v114, v0
	v_mov_b32_e32 v115, v0
	v_mov_b32_e32 v116, v0
	v_mov_b32_e32 v117, v0
	v_mov_b32_e32 v118, v0
	v_mov_b32_e32 v119, v0
	v_mov_b32_e32 v72, v0
	v_mov_b32_e32 v73, v0
	v_mov_b32_e32 v74, v0
	v_mov_b32_e32 v75, v0
	v_mov_b32_e32 v76, v0
	v_mov_b32_e32 v77, v0
	v_mov_b32_e32 v78, v0
	v_mov_b32_e32 v79, v0
	v_mov_b32_e32 v88, v0
	v_mov_b32_e32 v89, v0
	v_mov_b32_e32 v90, v0
	v_mov_b32_e32 v91, v0
	v_mov_b32_e32 v92, v0
	v_mov_b32_e32 v93, v0
	v_mov_b32_e32 v94, v0
	v_mov_b32_e32 v95, v0
	v_mov_b32_e32 v104, v0
	v_mov_b32_e32 v105, v0
	v_mov_b32_e32 v106, v0
	v_mov_b32_e32 v107, v0
	v_mov_b32_e32 v108, v0
	v_mov_b32_e32 v109, v0
	v_mov_b32_e32 v110, v0
	v_mov_b32_e32 v111, v0
	v_mov_b32_e32 v120, v0
	v_mov_b32_e32 v121, v0
	v_mov_b32_e32 v122, v0
	v_mov_b32_e32 v123, v0
	v_mov_b32_e32 v124, v0
	v_mov_b32_e32 v125, v0
	v_mov_b32_e32 v126, v0
	v_mov_b32_e32 v127, v0
	s_cmpk_lt_u32 s81, 0x100
	s_cbranch_scc1 .Lgprio_RECIN
	s_setprio 1
.Lgprio_RECIN:
.LBB0_478:
	s_add_u32 s20, s40, 0xfffc0080
	s_addc_u32 s21, s41, -1
	s_add_i32 s65, 0, 0x10000
	s_cmp_eq_u32 s64, 12
	s_cselect_b32 s43, s15, s21
	s_cselect_b32 s42, s45, s20
	v_add_u32_e32 v167, s65, v149
	s_cselect_b32 s21, s13, s63
	s_cselect_b32 s20, s61, s62
	s_add_i32 s68, 0, 0x14000
	ds_read_b128 v[140:143], v167
	ds_read_b128 v[144:147], v167 offset:1024
	ds_read_b128 v[170:173], v167 offset:2048
	ds_read_b128 v[174:177], v167 offset:3072
	v_add_u32_e32 v167, s68, v149
	ds_read_b128 v[178:181], v167
	ds_read_b128 v[182:185], v167 offset:1024
	ds_read_b128 v[186:189], v167 offset:2048
	ds_read_b128 v[190:193], v167 offset:3072
	v_lshl_add_u64 v[226:227], s[40:41], 0, v[138:139]
	s_add_i32 m0, s53, 0xc000
	ds_read_b128 v[194:197], v166
	ds_read_b128 v[198:201], v166 offset:1024
	ds_read_b128 v[202:205], v166 offset:2048
	ds_read_b128 v[206:209], v166 offset:3072
	ds_read_b128 v[210:213], v166 offset:4096
	ds_read_b128 v[214:217], v166 offset:5120
	ds_read_b128 v[218:221], v166 offset:6144
	ds_read_b128 v[222:225], v166 offset:7168
	global_load_lds_dwordx4 v[226:227], off
	v_lshl_add_u64 v[226:227], s[40:41], 0, v[136:137]
	s_add_i32 m0, s53, 0xe000
	s_nop 0
	global_load_lds_dwordx4 v[226:227], off
	s_waitcnt vmcnt(8)
	s_waitcnt lgkmcnt(0)
	s_barrier
	v_mfma_f32_16x16x32_bf16 v[124:127], v[140:143], v[194:197], v[124:127]
	v_mfma_f32_16x16x32_bf16 v[124:127], v[144:147], v[198:201], v[124:127]
	v_mfma_f32_16x16x32_bf16 v[120:123], v[170:173], v[194:197], v[120:123]
	v_mfma_f32_16x16x32_bf16 v[120:123], v[174:177], v[198:201], v[120:123]
	v_mfma_f32_16x16x32_bf16 v[108:111], v[140:143], v[202:205], v[108:111]
	v_mfma_f32_16x16x32_bf16 v[108:111], v[144:147], v[206:209], v[108:111]
	v_mfma_f32_16x16x32_bf16 v[104:107], v[170:173], v[202:205], v[104:107]
	v_mfma_f32_16x16x32_bf16 v[104:107], v[174:177], v[206:209], v[104:107]
	v_mfma_f32_16x16x32_bf16 v[92:95], v[140:143], v[210:213], v[92:95]
	v_mfma_f32_16x16x32_bf16 v[92:95], v[144:147], v[214:217], v[92:95]
	v_mfma_f32_16x16x32_bf16 v[88:91], v[170:173], v[210:213], v[88:91]
	v_mfma_f32_16x16x32_bf16 v[88:91], v[174:177], v[214:217], v[88:91]
	v_mfma_f32_16x16x32_bf16 v[76:79], v[140:143], v[218:221], v[76:79]
	v_mfma_f32_16x16x32_bf16 v[76:79], v[144:147], v[222:225], v[76:79]
	v_mfma_f32_16x16x32_bf16 v[72:75], v[170:173], v[218:221], v[72:75]
	v_mfma_f32_16x16x32_bf16 v[72:75], v[174:177], v[222:225], v[72:75]
	v_mfma_f32_16x16x32_bf16 v[116:119], v[178:181], v[194:197], v[116:119]
	v_mfma_f32_16x16x32_bf16 v[116:119], v[182:185], v[198:201], v[116:119]
	v_mfma_f32_16x16x32_bf16 v[112:115], v[186:189], v[194:197], v[112:115]
	v_mfma_f32_16x16x32_bf16 v[112:115], v[190:193], v[198:201], v[112:115]
	v_mfma_f32_16x16x32_bf16 v[100:103], v[178:181], v[202:205], v[100:103]
	v_mfma_f32_16x16x32_bf16 v[100:103], v[182:185], v[206:209], v[100:103]
	v_mfma_f32_16x16x32_bf16 v[96:99], v[186:189], v[202:205], v[96:99]
	v_mfma_f32_16x16x32_bf16 v[96:99], v[190:193], v[206:209], v[96:99]
	v_mfma_f32_16x16x32_bf16 v[84:87], v[178:181], v[210:213], v[84:87]
	v_mfma_f32_16x16x32_bf16 v[84:87], v[182:185], v[214:217], v[84:87]
	v_mfma_f32_16x16x32_bf16 v[80:83], v[186:189], v[210:213], v[80:83]
	v_mfma_f32_16x16x32_bf16 v[80:83], v[190:193], v[214:217], v[80:83]
	v_mfma_f32_16x16x32_bf16 v[68:71], v[178:181], v[218:221], v[68:71]
	v_mfma_f32_16x16x32_bf16 v[68:71], v[182:185], v[222:225], v[68:71]
	v_mfma_f32_16x16x32_bf16 v[64:67], v[186:189], v[218:221], v[64:67]
	v_mfma_f32_16x16x32_bf16 v[64:67], v[190:193], v[222:225], v[64:67]
	s_barrier
	s_add_i32 s65, s65, s50
	v_lshl_add_u64 v[226:227], s[20:21], 0, v[132:133]
	s_mov_b32 m0, s65
	ds_read_b128 v[194:197], v166 offset:16384
	ds_read_b128 v[198:201], v166 offset:17408
	ds_read_b128 v[202:205], v166 offset:18432
	ds_read_b128 v[206:209], v166 offset:19456
	ds_read_b128 v[210:213], v166 offset:20480
	ds_read_b128 v[214:217], v166 offset:21504
	ds_read_b128 v[218:221], v166 offset:22528
	ds_read_b128 v[222:225], v166 offset:23552
	global_load_lds_dwordx4 v[226:227], off
	s_add_i32 m0, s65, 0x2000
	s_add_u32 s66, s20, 0x40000
	v_lshl_add_u64 v[228:229], s[20:21], 0, v[128:129]
	s_addc_u32 s67, s21, 0
	s_add_i32 s65, s68, s50
	global_load_lds_dwordx4 v[228:229], off
	v_lshl_add_u64 v[230:231], s[66:67], 0, v[132:133]
	s_mov_b32 m0, s65
	v_lshl_add_u64 v[232:233], s[42:43], 0, v[130:131]
	global_load_lds_dwordx4 v[230:231], off
	v_lshl_add_u64 v[230:231], s[66:67], 0, v[128:129]
	s_add_i32 m0, s65, 0x2000
	s_nop 0
	global_load_lds_dwordx4 v[230:231], off
	v_lshl_add_u64 v[230:231], s[42:43], 0, v[134:135]
	s_mov_b32 m0, s53
	s_nop 0
	global_load_lds_dwordx4 v[230:231], off
	s_mov_b32 m0, s54
	s_nop 0
	global_load_lds_dwordx4 v[232:233], off
	s_waitcnt vmcnt(8)
	s_waitcnt lgkmcnt(0)
	s_barrier
	v_mfma_f32_16x16x32_bf16 v[60:63], v[140:143], v[194:197], v[60:63]
	v_mfma_f32_16x16x32_bf16 v[60:63], v[144:147], v[198:201], v[60:63]
	v_mfma_f32_16x16x32_bf16 v[56:59], v[170:173], v[194:197], v[56:59]
	v_mfma_f32_16x16x32_bf16 v[56:59], v[174:177], v[198:201], v[56:59]
	v_mfma_f32_16x16x32_bf16 v[44:47], v[140:143], v[202:205], v[44:47]
	v_mfma_f32_16x16x32_bf16 v[44:47], v[144:147], v[206:209], v[44:47]
	v_mfma_f32_16x16x32_bf16 v[40:43], v[170:173], v[202:205], v[40:43]
	v_mfma_f32_16x16x32_bf16 v[40:43], v[174:177], v[206:209], v[40:43]
	v_mfma_f32_16x16x32_bf16 v[28:31], v[140:143], v[210:213], v[28:31]
	v_mfma_f32_16x16x32_bf16 v[28:31], v[144:147], v[214:217], v[28:31]
	v_mfma_f32_16x16x32_bf16 v[24:27], v[170:173], v[210:213], v[24:27]
	v_mfma_f32_16x16x32_bf16 v[24:27], v[174:177], v[214:217], v[24:27]
	v_mfma_f32_16x16x32_bf16 v[12:15], v[140:143], v[218:221], v[12:15]
	v_mfma_f32_16x16x32_bf16 v[12:15], v[144:147], v[222:225], v[12:15]
	v_mfma_f32_16x16x32_bf16 v[8:11], v[170:173], v[218:221], v[8:11]
	v_mfma_f32_16x16x32_bf16 v[8:11], v[174:177], v[222:225], v[8:11]
	v_mfma_f32_16x16x32_bf16 v[52:55], v[178:181], v[194:197], v[52:55]
	v_mfma_f32_16x16x32_bf16 v[52:55], v[182:185], v[198:201], v[52:55]
	v_mfma_f32_16x16x32_bf16 v[48:51], v[186:189], v[194:197], v[48:51]
	v_mfma_f32_16x16x32_bf16 v[48:51], v[190:193], v[198:201], v[48:51]
	v_mfma_f32_16x16x32_bf16 v[36:39], v[178:181], v[202:205], v[36:39]
	v_mfma_f32_16x16x32_bf16 v[36:39], v[182:185], v[206:209], v[36:39]
	v_mfma_f32_16x16x32_bf16 v[32:35], v[186:189], v[202:205], v[32:35]
	v_mfma_f32_16x16x32_bf16 v[32:35], v[190:193], v[206:209], v[32:35]
	v_mfma_f32_16x16x32_bf16 v[20:23], v[178:181], v[210:213], v[20:23]
	v_mfma_f32_16x16x32_bf16 v[20:23], v[182:185], v[214:217], v[20:23]
	v_mfma_f32_16x16x32_bf16 v[16:19], v[186:189], v[210:213], v[16:19]
	v_mfma_f32_16x16x32_bf16 v[16:19], v[190:193], v[214:217], v[16:19]
	v_mfma_f32_16x16x32_bf16 v[4:7], v[178:181], v[218:221], v[4:7]
	v_mfma_f32_16x16x32_bf16 v[4:7], v[182:185], v[222:225], v[4:7]
	v_mfma_f32_16x16x32_bf16 v[0:3], v[186:189], v[218:221], v[0:3]
	v_mfma_f32_16x16x32_bf16 v[0:3], v[190:193], v[222:225], v[0:3]
	s_barrier
	s_add_i32 s65, 0, 0x18000
	v_add_u32_e32 v167, s65, v149
	s_add_i32 s66, 0, 0x1c000
	ds_read_b128 v[140:143], v167
	ds_read_b128 v[144:147], v167 offset:1024
	ds_read_b128 v[170:173], v167 offset:2048
	ds_read_b128 v[174:177], v167 offset:3072
	v_add_u32_e32 v167, s66, v149
	ds_read_b128 v[178:181], v167
	ds_read_b128 v[182:185], v167 offset:1024
	ds_read_b128 v[186:189], v167 offset:2048
	ds_read_b128 v[190:193], v167 offset:3072
	s_add_u32 s42, s42, 0x40000
	s_addc_u32 s43, s43, 0
	s_mov_b32 m0, s55
	v_lshl_add_u64 v[234:235], s[42:43], 0, v[134:135]
	ds_read_b128 v[194:197], v166 offset:32768
	ds_read_b128 v[198:201], v166 offset:33792
	ds_read_b128 v[202:205], v166 offset:34816
	ds_read_b128 v[206:209], v166 offset:35840
	ds_read_b128 v[210:213], v166 offset:36864
	ds_read_b128 v[214:217], v166 offset:37888
	ds_read_b128 v[218:221], v166 offset:38912
	ds_read_b128 v[222:225], v166 offset:39936
	global_load_lds_dwordx4 v[234:235], off
	v_lshl_add_u64 v[234:235], s[42:43], 0, v[130:131]
	s_mov_b32 m0, s56
	s_nop 0
	global_load_lds_dwordx4 v[234:235], off
	s_waitcnt vmcnt(8)
	s_waitcnt lgkmcnt(0)
	s_barrier
	v_mfma_f32_16x16x32_bf16 v[124:127], v[140:143], v[194:197], v[124:127]
	v_mfma_f32_16x16x32_bf16 v[124:127], v[144:147], v[198:201], v[124:127]
	v_mfma_f32_16x16x32_bf16 v[120:123], v[170:173], v[194:197], v[120:123]
	v_mfma_f32_16x16x32_bf16 v[120:123], v[174:177], v[198:201], v[120:123]
	v_mfma_f32_16x16x32_bf16 v[108:111], v[140:143], v[202:205], v[108:111]
	v_mfma_f32_16x16x32_bf16 v[108:111], v[144:147], v[206:209], v[108:111]
	v_mfma_f32_16x16x32_bf16 v[104:107], v[170:173], v[202:205], v[104:107]
	v_mfma_f32_16x16x32_bf16 v[104:107], v[174:177], v[206:209], v[104:107]
	v_mfma_f32_16x16x32_bf16 v[92:95], v[140:143], v[210:213], v[92:95]
	v_mfma_f32_16x16x32_bf16 v[92:95], v[144:147], v[214:217], v[92:95]
	v_mfma_f32_16x16x32_bf16 v[88:91], v[170:173], v[210:213], v[88:91]
	v_mfma_f32_16x16x32_bf16 v[88:91], v[174:177], v[214:217], v[88:91]
	v_mfma_f32_16x16x32_bf16 v[76:79], v[140:143], v[218:221], v[76:79]
	v_mfma_f32_16x16x32_bf16 v[76:79], v[144:147], v[222:225], v[76:79]
	v_mfma_f32_16x16x32_bf16 v[72:75], v[170:173], v[218:221], v[72:75]
	v_mfma_f32_16x16x32_bf16 v[72:75], v[174:177], v[222:225], v[72:75]
	v_mfma_f32_16x16x32_bf16 v[116:119], v[178:181], v[194:197], v[116:119]
	v_mfma_f32_16x16x32_bf16 v[116:119], v[182:185], v[198:201], v[116:119]
	v_mfma_f32_16x16x32_bf16 v[112:115], v[186:189], v[194:197], v[112:115]
	v_mfma_f32_16x16x32_bf16 v[112:115], v[190:193], v[198:201], v[112:115]
	v_mfma_f32_16x16x32_bf16 v[100:103], v[178:181], v[202:205], v[100:103]
	v_mfma_f32_16x16x32_bf16 v[100:103], v[182:185], v[206:209], v[100:103]
	v_mfma_f32_16x16x32_bf16 v[96:99], v[186:189], v[202:205], v[96:99]
	v_mfma_f32_16x16x32_bf16 v[96:99], v[190:193], v[206:209], v[96:99]
	v_mfma_f32_16x16x32_bf16 v[84:87], v[178:181], v[210:213], v[84:87]
	v_mfma_f32_16x16x32_bf16 v[84:87], v[182:185], v[214:217], v[84:87]
	v_mfma_f32_16x16x32_bf16 v[80:83], v[186:189], v[210:213], v[80:83]
	v_mfma_f32_16x16x32_bf16 v[80:83], v[190:193], v[214:217], v[80:83]
	v_mfma_f32_16x16x32_bf16 v[68:71], v[178:181], v[218:221], v[68:71]
	v_mfma_f32_16x16x32_bf16 v[68:71], v[182:185], v[222:225], v[68:71]
	v_mfma_f32_16x16x32_bf16 v[64:67], v[186:189], v[218:221], v[64:67]
	v_mfma_f32_16x16x32_bf16 v[64:67], v[190:193], v[222:225], v[64:67]
	s_barrier
	s_add_i32 s42, s65, s50
	v_lshl_add_u64 v[226:227], v[226:227], 0, s[36:37]
	s_mov_b32 m0, s42
	ds_read_b128 v[194:197], v166 offset:49152
	ds_read_b128 v[198:201], v166 offset:50176
	ds_read_b128 v[202:205], v166 offset:51200
	ds_read_b128 v[206:209], v166 offset:52224
	ds_read_b128 v[210:213], v166 offset:53248
	ds_read_b128 v[214:217], v166 offset:54272
	ds_read_b128 v[218:221], v166 offset:55296
	ds_read_b128 v[222:225], v166 offset:56320
	global_load_lds_dwordx4 v[226:227], off
	s_add_i32 m0, s42, 0x2000
	s_add_u32 s20, s20, 0x40080
	v_lshl_add_u64 v[226:227], v[228:229], 0, s[36:37]
	s_addc_u32 s21, s21, 0
	s_add_i32 s42, s66, s50
	global_load_lds_dwordx4 v[226:227], off
	v_lshl_add_u64 v[226:227], s[20:21], 0, v[132:133]
	s_mov_b32 m0, s42
	s_nop 0
	global_load_lds_dwordx4 v[226:227], off
	v_lshl_add_u64 v[226:227], s[20:21], 0, v[128:129]
	s_add_i32 m0, s42, 0x2000
	s_nop 0
	global_load_lds_dwordx4 v[226:227], off
	v_lshl_add_u64 v[226:227], v[230:231], 0, s[36:37]
	s_mov_b32 m0, s57
	s_nop 0
	global_load_lds_dwordx4 v[226:227], off
	v_lshl_add_u64 v[226:227], v[232:233], 0, s[36:37]
	s_mov_b32 m0, s58
	s_nop 0
	global_load_lds_dwordx4 v[226:227], off
	s_waitcnt vmcnt(8)
	s_waitcnt lgkmcnt(0)
	s_barrier
	v_mfma_f32_16x16x32_bf16 v[60:63], v[140:143], v[194:197], v[60:63]
	v_mfma_f32_16x16x32_bf16 v[60:63], v[144:147], v[198:201], v[60:63]
	v_mfma_f32_16x16x32_bf16 v[56:59], v[170:173], v[194:197], v[56:59]
	v_mfma_f32_16x16x32_bf16 v[56:59], v[174:177], v[198:201], v[56:59]
	v_mfma_f32_16x16x32_bf16 v[44:47], v[140:143], v[202:205], v[44:47]
	v_mfma_f32_16x16x32_bf16 v[44:47], v[144:147], v[206:209], v[44:47]
	v_mfma_f32_16x16x32_bf16 v[40:43], v[170:173], v[202:205], v[40:43]
	v_mfma_f32_16x16x32_bf16 v[40:43], v[174:177], v[206:209], v[40:43]
	v_mfma_f32_16x16x32_bf16 v[28:31], v[140:143], v[210:213], v[28:31]
	v_mfma_f32_16x16x32_bf16 v[28:31], v[144:147], v[214:217], v[28:31]
	v_mfma_f32_16x16x32_bf16 v[24:27], v[170:173], v[210:213], v[24:27]
	v_mfma_f32_16x16x32_bf16 v[24:27], v[174:177], v[214:217], v[24:27]
	v_mfma_f32_16x16x32_bf16 v[12:15], v[140:143], v[218:221], v[12:15]
	v_mfma_f32_16x16x32_bf16 v[12:15], v[144:147], v[222:225], v[12:15]
	v_mfma_f32_16x16x32_bf16 v[8:11], v[170:173], v[218:221], v[8:11]
	v_mfma_f32_16x16x32_bf16 v[8:11], v[174:177], v[222:225], v[8:11]
	v_mfma_f32_16x16x32_bf16 v[52:55], v[178:181], v[194:197], v[52:55]
	v_mfma_f32_16x16x32_bf16 v[52:55], v[182:185], v[198:201], v[52:55]
	v_mfma_f32_16x16x32_bf16 v[48:51], v[186:189], v[194:197], v[48:51]
	v_mfma_f32_16x16x32_bf16 v[48:51], v[190:193], v[198:201], v[48:51]
	v_mfma_f32_16x16x32_bf16 v[36:39], v[178:181], v[202:205], v[36:39]
	v_mfma_f32_16x16x32_bf16 v[36:39], v[182:185], v[206:209], v[36:39]
	v_mfma_f32_16x16x32_bf16 v[32:35], v[186:189], v[202:205], v[32:35]
	v_mfma_f32_16x16x32_bf16 v[32:35], v[190:193], v[206:209], v[32:35]
	v_mfma_f32_16x16x32_bf16 v[20:23], v[178:181], v[210:213], v[20:23]
	v_mfma_f32_16x16x32_bf16 v[20:23], v[182:185], v[214:217], v[20:23]
	v_mfma_f32_16x16x32_bf16 v[16:19], v[186:189], v[210:213], v[16:19]
	v_mfma_f32_16x16x32_bf16 v[16:19], v[190:193], v[214:217], v[16:19]
	v_mfma_f32_16x16x32_bf16 v[4:7], v[178:181], v[218:221], v[4:7]
	v_mfma_f32_16x16x32_bf16 v[4:7], v[182:185], v[222:225], v[4:7]
	v_mfma_f32_16x16x32_bf16 v[0:3], v[186:189], v[218:221], v[0:3]
	v_mfma_f32_16x16x32_bf16 v[0:3], v[190:193], v[222:225], v[0:3]
	s_barrier
	s_add_i32 s64, s64, 2
	s_add_u32 s62, s62, 0x100
	s_addc_u32 s63, s63, 0
	s_add_u32 s40, s40, 0x100
	s_addc_u32 s41, s41, 0
	s_cmp_gt_u32 s64, 13
	s_cbranch_scc0 .LBB0_478
	s_setprio 0
	s_and_b64 vcc, exec, s[8:9]
	s_cbranch_vccz .LBB0_481
	s_barrier

.LBB0_574:
	s_add_u32 s44, s44, 0x100
	s_addc_u32 s45, s45, 0
	s_add_u32 s42, s54, 0x80
	v_mov_b32_e32 v0, 0
	s_addc_u32 s43, s55, 0
	s_mov_b32 s20, 0
	v_mov_b32_e32 v1, v0
	v_mov_b32_e32 v2, v0
	v_mov_b32_e32 v3, v0
	v_mov_b32_e32 v4, v0
	v_mov_b32_e32 v5, v0
	v_mov_b32_e32 v6, v0
	v_mov_b32_e32 v7, v0
	v_mov_b32_e32 v16, v0
	v_mov_b32_e32 v17, v0
	v_mov_b32_e32 v18, v0
	v_mov_b32_e32 v19, v0
	v_mov_b32_e32 v20, v0
	v_mov_b32_e32 v21, v0
	v_mov_b32_e32 v22, v0
	v_mov_b32_e32 v23, v0
	v_mov_b32_e32 v32, v0
	v_mov_b32_e32 v33, v0
	v_mov_b32_e32 v34, v0
	v_mov_b32_e32 v35, v0
	v_mov_b32_e32 v36, v0
	v_mov_b32_e32 v37, v0
	v_mov_b32_e32 v38, v0
	v_mov_b32_e32 v39, v0
	v_mov_b32_e32 v48, v0
	v_mov_b32_e32 v49, v0
	v_mov_b32_e32 v50, v0
	v_mov_b32_e32 v51, v0
	v_mov_b32_e32 v52, v0
	v_mov_b32_e32 v53, v0
	v_mov_b32_e32 v54, v0
	v_mov_b32_e32 v55, v0
	v_mov_b32_e32 v8, v0
	v_mov_b32_e32 v9, v0
	v_mov_b32_e32 v10, v0
	v_mov_b32_e32 v11, v0
	v_mov_b32_e32 v12, v0
	v_mov_b32_e32 v13, v0
	v_mov_b32_e32 v14, v0
	v_mov_b32_e32 v15, v0
	v_mov_b32_e32 v24, v0
	v_mov_b32_e32 v25, v0
	v_mov_b32_e32 v26, v0
	v_mov_b32_e32 v27, v0
	v_mov_b32_e32 v28, v0
	v_mov_b32_e32 v29, v0
	v_mov_b32_e32 v30, v0
	v_mov_b32_e32 v31, v0
	v_mov_b32_e32 v40, v0
	v_mov_b32_e32 v41, v0
	v_mov_b32_e32 v42, v0
	v_mov_b32_e32 v43, v0
	v_mov_b32_e32 v44, v0
	v_mov_b32_e32 v45, v0
	v_mov_b32_e32 v46, v0
	v_mov_b32_e32 v47, v0
	v_mov_b32_e32 v56, v0
	v_mov_b32_e32 v57, v0
	v_mov_b32_e32 v58, v0
	v_mov_b32_e32 v59, v0
	v_mov_b32_e32 v60, v0
	v_mov_b32_e32 v61, v0
	v_mov_b32_e32 v62, v0
	v_mov_b32_e32 v63, v0
	v_mov_b32_e32 v64, v0
	v_mov_b32_e32 v65, v0
	v_mov_b32_e32 v66, v0
	v_mov_b32_e32 v67, v0
	v_mov_b32_e32 v68, v0
	v_mov_b32_e32 v69, v0
	v_mov_b32_e32 v70, v0
	v_mov_b32_e32 v71, v0
	v_mov_b32_e32 v80, v0
	v_mov_b32_e32 v81, v0
	v_mov_b32_e32 v82, v0
	v_mov_b32_e32 v83, v0
	v_mov_b32_e32 v84, v0
	v_mov_b32_e32 v85, v0
	v_mov_b32_e32 v86, v0
	v_mov_b32_e32 v87, v0
	v_mov_b32_e32 v104, v0
	v_mov_b32_e32 v105, v0
	v_mov_b32_e32 v106, v0
	v_mov_b32_e32 v107, v0
	v_mov_b32_e32 v108, v0
	v_mov_b32_e32 v109, v0
	v_mov_b32_e32 v110, v0
	v_mov_b32_e32 v111, v0
	v_mov_b32_e32 v128, v0
	v_mov_b32_e32 v129, v0
	v_mov_b32_e32 v130, v0
	v_mov_b32_e32 v131, v0
	v_mov_b32_e32 v132, v0
	v_mov_b32_e32 v133, v0
	v_mov_b32_e32 v134, v0
	v_mov_b32_e32 v135, v0
	v_mov_b32_e32 v72, v0
	v_mov_b32_e32 v73, v0
	v_mov_b32_e32 v74, v0
	v_mov_b32_e32 v75, v0
	v_mov_b32_e32 v76, v0
	v_mov_b32_e32 v77, v0
	v_mov_b32_e32 v78, v0
	v_mov_b32_e32 v79, v0
	v_mov_b32_e32 v92, v0
	v_mov_b32_e32 v93, v0
	v_mov_b32_e32 v94, v0
	v_mov_b32_e32 v95, v0
	v_mov_b32_e32 v96, v0
	v_mov_b32_e32 v97, v0
	v_mov_b32_e32 v98, v0
	v_mov_b32_e32 v99, v0
	v_mov_b32_e32 v116, v0
	v_mov_b32_e32 v117, v0
	v_mov_b32_e32 v118, v0
	v_mov_b32_e32 v119, v0
	v_mov_b32_e32 v120, v0
	v_mov_b32_e32 v121, v0
	v_mov_b32_e32 v122, v0
	v_mov_b32_e32 v123, v0
	v_mov_b32_e32 v140, v0
	v_mov_b32_e32 v141, v0
	v_mov_b32_e32 v142, v0
	v_mov_b32_e32 v143, v0
	v_mov_b32_e32 v144, v0
	v_mov_b32_e32 v145, v0
	v_mov_b32_e32 v146, v0
	v_mov_b32_e32 v147, v0
	s_cmpk_lt_u32 s81, 0x100
	s_cbranch_scc1 .Lgprio_DOWN
	s_setprio 1
.Lgprio_DOWN:
.LBB0_575:
	s_add_i32 s54, s20, 2
	s_add_u32 s55, s42, 0x80
	s_addc_u32 s21, s43, 0
	s_add_i32 s74, 0, 0x10000
	s_cmp_eq_u32 s31, s20
	s_cselect_b32 s21, s51, s21
	s_cselect_b32 s20, s50, s55
	s_cselect_b32 s73, s53, s45
	s_cselect_b32 s72, s52, s44
	s_add_i32 s55, 0, 0x14000
	v_add_u32_e32 v124, s74, v207
	v_add_u32_e32 v166, s55, v207
	ds_read_b128 v[88:91], v124
	ds_read_b128 v[100:103], v124 offset:1024
	ds_read_b128 v[112:115], v124 offset:2048
	ds_read_b128 v[124:127], v124 offset:3072
	ds_read_b128 v[136:139], v166
	ds_read_b128 v[148:151], v166 offset:1024
	ds_read_b128 v[152:155], v166 offset:2048
	ds_read_b128 v[170:173], v166 offset:3072
	v_lshl_add_u64 v[166:167], s[42:43], 0, v[164:165]
	s_add_i32 m0, s61, 0xc000
	ds_read_b128 v[174:177], v211
	ds_read_b128 v[178:181], v211 offset:1024
	ds_read_b128 v[182:185], v211 offset:2048
	ds_read_b128 v[186:189], v211 offset:3072
	ds_read_b128 v[190:193], v211 offset:4096
	ds_read_b128 v[194:197], v211 offset:5120
	ds_read_b128 v[198:201], v211 offset:6144
	ds_read_b128 v[202:205], v211 offset:7168
	global_load_lds_dwordx4 v[166:167], off
	v_lshl_add_u64 v[166:167], s[42:43], 0, v[162:163]
	s_add_i32 m0, s61, 0xe000
	s_nop 0
	global_load_lds_dwordx4 v[166:167], off
	s_waitcnt vmcnt(8)
	s_waitcnt lgkmcnt(0)
	s_barrier
	v_mfma_f32_16x16x32_bf16 v[144:147], v[88:91], v[174:177], v[144:147]
	v_mfma_f32_16x16x32_bf16 v[144:147], v[100:103], v[178:181], v[144:147]
	v_mfma_f32_16x16x32_bf16 v[140:143], v[112:115], v[174:177], v[140:143]
	v_mfma_f32_16x16x32_bf16 v[140:143], v[124:127], v[178:181], v[140:143]
	v_mfma_f32_16x16x32_bf16 v[120:123], v[88:91], v[182:185], v[120:123]
	v_mfma_f32_16x16x32_bf16 v[120:123], v[100:103], v[186:189], v[120:123]
	v_mfma_f32_16x16x32_bf16 v[116:119], v[112:115], v[182:185], v[116:119]
	v_mfma_f32_16x16x32_bf16 v[116:119], v[124:127], v[186:189], v[116:119]
	v_mfma_f32_16x16x32_bf16 v[96:99], v[88:91], v[190:193], v[96:99]
	v_mfma_f32_16x16x32_bf16 v[96:99], v[100:103], v[194:197], v[96:99]
	v_mfma_f32_16x16x32_bf16 v[92:95], v[112:115], v[190:193], v[92:95]
	v_mfma_f32_16x16x32_bf16 v[92:95], v[124:127], v[194:197], v[92:95]
	v_mfma_f32_16x16x32_bf16 v[76:79], v[88:91], v[198:201], v[76:79]
	v_mfma_f32_16x16x32_bf16 v[76:79], v[100:103], v[202:205], v[76:79]
	v_mfma_f32_16x16x32_bf16 v[72:75], v[112:115], v[198:201], v[72:75]
	v_mfma_f32_16x16x32_bf16 v[72:75], v[124:127], v[202:205], v[72:75]
	v_mfma_f32_16x16x32_bf16 v[132:135], v[136:139], v[174:177], v[132:135]
	v_mfma_f32_16x16x32_bf16 v[132:135], v[148:151], v[178:181], v[132:135]
	v_mfma_f32_16x16x32_bf16 v[128:131], v[152:155], v[174:177], v[128:131]
	v_mfma_f32_16x16x32_bf16 v[128:131], v[170:173], v[178:181], v[128:131]
	v_mfma_f32_16x16x32_bf16 v[108:111], v[136:139], v[182:185], v[108:111]
	v_mfma_f32_16x16x32_bf16 v[108:111], v[148:151], v[186:189], v[108:111]
	v_mfma_f32_16x16x32_bf16 v[104:107], v[152:155], v[182:185], v[104:107]
	v_mfma_f32_16x16x32_bf16 v[104:107], v[170:173], v[186:189], v[104:107]
	v_mfma_f32_16x16x32_bf16 v[84:87], v[136:139], v[190:193], v[84:87]
	v_mfma_f32_16x16x32_bf16 v[84:87], v[148:151], v[194:197], v[84:87]
	v_mfma_f32_16x16x32_bf16 v[80:83], v[152:155], v[190:193], v[80:83]
	v_mfma_f32_16x16x32_bf16 v[80:83], v[170:173], v[194:197], v[80:83]
	v_mfma_f32_16x16x32_bf16 v[68:71], v[136:139], v[198:201], v[68:71]
	v_mfma_f32_16x16x32_bf16 v[68:71], v[148:151], v[202:205], v[68:71]
	v_mfma_f32_16x16x32_bf16 v[64:67], v[152:155], v[198:201], v[64:67]
	v_mfma_f32_16x16x32_bf16 v[64:67], v[170:173], v[202:205], v[64:67]
	s_barrier
	s_add_i32 s74, s74, s56
	v_lshl_add_u64 v[166:167], s[72:73], 0, v[168:169]
	s_mov_b32 m0, s74
	ds_read_b128 v[174:177], v211 offset:16384
	ds_read_b128 v[178:181], v211 offset:17408
	ds_read_b128 v[182:185], v211 offset:18432
	ds_read_b128 v[186:189], v211 offset:19456
	ds_read_b128 v[190:193], v211 offset:20480
	ds_read_b128 v[194:197], v211 offset:21504
	ds_read_b128 v[198:201], v211 offset:22528
	ds_read_b128 v[202:205], v211 offset:23552
	global_load_lds_dwordx4 v[166:167], off
	s_add_i32 m0, s74, 0x2000
	v_lshl_add_u64 v[212:213], s[72:73], 0, v[156:157]
	s_add_u32 s72, s72, s0
	s_addc_u32 s73, s73, 0
	s_add_i32 s55, s55, s56
	global_load_lds_dwordx4 v[212:213], off
	v_lshl_add_u64 v[214:215], s[72:73], 0, v[168:169]
	s_mov_b32 m0, s55
	v_lshl_add_u64 v[216:217], s[72:73], 0, v[156:157]
	global_load_lds_dwordx4 v[214:215], off
	s_add_i32 m0, s55, 0x2000
	v_lshl_add_u64 v[218:219], s[20:21], 0, v[160:161]
	global_load_lds_dwordx4 v[216:217], off
	s_mov_b32 m0, s61
	v_lshl_add_u64 v[220:221], s[20:21], 0, v[158:159]
	global_load_lds_dwordx4 v[218:219], off
	s_mov_b32 m0, s62
	s_nop 0
	global_load_lds_dwordx4 v[220:221], off
	s_waitcnt vmcnt(8)
	s_waitcnt lgkmcnt(0)
	s_barrier
	v_mfma_f32_16x16x32_bf16 v[60:63], v[88:91], v[174:177], v[60:63]
	v_mfma_f32_16x16x32_bf16 v[60:63], v[100:103], v[178:181], v[60:63]
	v_mfma_f32_16x16x32_bf16 v[56:59], v[112:115], v[174:177], v[56:59]
	v_mfma_f32_16x16x32_bf16 v[56:59], v[124:127], v[178:181], v[56:59]
	v_mfma_f32_16x16x32_bf16 v[44:47], v[88:91], v[182:185], v[44:47]
	v_mfma_f32_16x16x32_bf16 v[44:47], v[100:103], v[186:189], v[44:47]
	v_mfma_f32_16x16x32_bf16 v[40:43], v[112:115], v[182:185], v[40:43]
	v_mfma_f32_16x16x32_bf16 v[40:43], v[124:127], v[186:189], v[40:43]
	v_mfma_f32_16x16x32_bf16 v[28:31], v[88:91], v[190:193], v[28:31]
	v_mfma_f32_16x16x32_bf16 v[28:31], v[100:103], v[194:197], v[28:31]
	v_mfma_f32_16x16x32_bf16 v[24:27], v[112:115], v[190:193], v[24:27]
	v_mfma_f32_16x16x32_bf16 v[24:27], v[124:127], v[194:197], v[24:27]
	v_mfma_f32_16x16x32_bf16 v[12:15], v[88:91], v[198:201], v[12:15]
	v_mfma_f32_16x16x32_bf16 v[12:15], v[100:103], v[202:205], v[12:15]
	v_mfma_f32_16x16x32_bf16 v[8:11], v[112:115], v[198:201], v[8:11]
	v_mfma_f32_16x16x32_bf16 v[8:11], v[124:127], v[202:205], v[8:11]
	v_mfma_f32_16x16x32_bf16 v[52:55], v[136:139], v[174:177], v[52:55]
	v_mfma_f32_16x16x32_bf16 v[52:55], v[148:151], v[178:181], v[52:55]
	v_mfma_f32_16x16x32_bf16 v[48:51], v[152:155], v[174:177], v[48:51]
	v_mfma_f32_16x16x32_bf16 v[48:51], v[170:173], v[178:181], v[48:51]
	v_mfma_f32_16x16x32_bf16 v[36:39], v[136:139], v[182:185], v[36:39]
	v_mfma_f32_16x16x32_bf16 v[36:39], v[148:151], v[186:189], v[36:39]
	v_mfma_f32_16x16x32_bf16 v[32:35], v[152:155], v[182:185], v[32:35]
	v_mfma_f32_16x16x32_bf16 v[32:35], v[170:173], v[186:189], v[32:35]
	v_mfma_f32_16x16x32_bf16 v[20:23], v[136:139], v[190:193], v[20:23]
	v_mfma_f32_16x16x32_bf16 v[20:23], v[148:151], v[194:197], v[20:23]
	v_mfma_f32_16x16x32_bf16 v[16:19], v[152:155], v[190:193], v[16:19]
	v_mfma_f32_16x16x32_bf16 v[16:19], v[170:173], v[194:197], v[16:19]
	v_mfma_f32_16x16x32_bf16 v[4:7], v[136:139], v[198:201], v[4:7]
	v_mfma_f32_16x16x32_bf16 v[4:7], v[148:151], v[202:205], v[4:7]
	v_mfma_f32_16x16x32_bf16 v[0:3], v[152:155], v[198:201], v[0:3]
	v_mfma_f32_16x16x32_bf16 v[0:3], v[170:173], v[202:205], v[0:3]
	s_barrier
	s_add_i32 s55, 0, 0x18000
	s_add_i32 s72, 0, 0x1c000
	v_add_u32_e32 v124, s55, v207
	v_add_u32_e32 v170, s72, v207
	ds_read_b128 v[88:91], v124
	ds_read_b128 v[100:103], v124 offset:1024
	ds_read_b128 v[112:115], v124 offset:2048
	ds_read_b128 v[124:127], v124 offset:3072
	ds_read_b128 v[136:139], v170
	ds_read_b128 v[148:151], v170 offset:1024
	ds_read_b128 v[152:155], v170 offset:2048
	ds_read_b128 v[170:173], v170 offset:3072
	s_add_u32 s20, s20, s0
	s_addc_u32 s21, s21, 0
	s_mov_b32 m0, s63
	v_lshl_add_u64 v[222:223], s[20:21], 0, v[160:161]
	ds_read_b128 v[174:177], v211 offset:32768
	ds_read_b128 v[178:181], v211 offset:33792
	ds_read_b128 v[182:185], v211 offset:34816
	ds_read_b128 v[186:189], v211 offset:35840
	ds_read_b128 v[190:193], v211 offset:36864
	ds_read_b128 v[194:197], v211 offset:37888
	ds_read_b128 v[198:201], v211 offset:38912
	ds_read_b128 v[202:205], v211 offset:39936
	global_load_lds_dwordx4 v[222:223], off
	v_lshl_add_u64 v[222:223], s[20:21], 0, v[158:159]
	s_mov_b32 m0, s64
	s_nop 0
	global_load_lds_dwordx4 v[222:223], off
	s_waitcnt vmcnt(8)
	s_waitcnt lgkmcnt(0)
	s_barrier
	v_mfma_f32_16x16x32_bf16 v[144:147], v[88:91], v[174:177], v[144:147]
	v_mfma_f32_16x16x32_bf16 v[144:147], v[100:103], v[178:181], v[144:147]
	v_mfma_f32_16x16x32_bf16 v[140:143], v[112:115], v[174:177], v[140:143]
	v_mfma_f32_16x16x32_bf16 v[140:143], v[124:127], v[178:181], v[140:143]
	v_mfma_f32_16x16x32_bf16 v[120:123], v[88:91], v[182:185], v[120:123]
	v_mfma_f32_16x16x32_bf16 v[120:123], v[100:103], v[186:189], v[120:123]
	v_mfma_f32_16x16x32_bf16 v[116:119], v[112:115], v[182:185], v[116:119]
	v_mfma_f32_16x16x32_bf16 v[116:119], v[124:127], v[186:189], v[116:119]
	v_mfma_f32_16x16x32_bf16 v[96:99], v[88:91], v[190:193], v[96:99]
	v_mfma_f32_16x16x32_bf16 v[96:99], v[100:103], v[194:197], v[96:99]
	v_mfma_f32_16x16x32_bf16 v[92:95], v[112:115], v[190:193], v[92:95]
	v_mfma_f32_16x16x32_bf16 v[92:95], v[124:127], v[194:197], v[92:95]
	v_mfma_f32_16x16x32_bf16 v[76:79], v[88:91], v[198:201], v[76:79]
	v_mfma_f32_16x16x32_bf16 v[76:79], v[100:103], v[202:205], v[76:79]
	v_mfma_f32_16x16x32_bf16 v[72:75], v[112:115], v[198:201], v[72:75]
	v_mfma_f32_16x16x32_bf16 v[72:75], v[124:127], v[202:205], v[72:75]
	v_mfma_f32_16x16x32_bf16 v[132:135], v[136:139], v[174:177], v[132:135]
	v_mfma_f32_16x16x32_bf16 v[132:135], v[148:151], v[178:181], v[132:135]
	v_mfma_f32_16x16x32_bf16 v[128:131], v[152:155], v[174:177], v[128:131]
	v_mfma_f32_16x16x32_bf16 v[128:131], v[170:173], v[178:181], v[128:131]
	v_mfma_f32_16x16x32_bf16 v[108:111], v[136:139], v[182:185], v[108:111]
	v_mfma_f32_16x16x32_bf16 v[108:111], v[148:151], v[186:189], v[108:111]
	v_mfma_f32_16x16x32_bf16 v[104:107], v[152:155], v[182:185], v[104:107]
	v_mfma_f32_16x16x32_bf16 v[104:107], v[170:173], v[186:189], v[104:107]
	v_mfma_f32_16x16x32_bf16 v[84:87], v[136:139], v[190:193], v[84:87]
	v_mfma_f32_16x16x32_bf16 v[84:87], v[148:151], v[194:197], v[84:87]
	v_mfma_f32_16x16x32_bf16 v[80:83], v[152:155], v[190:193], v[80:83]
	v_mfma_f32_16x16x32_bf16 v[80:83], v[170:173], v[194:197], v[80:83]
	v_mfma_f32_16x16x32_bf16 v[68:71], v[136:139], v[198:201], v[68:71]
	v_mfma_f32_16x16x32_bf16 v[68:71], v[148:151], v[202:205], v[68:71]
	v_mfma_f32_16x16x32_bf16 v[64:67], v[152:155], v[198:201], v[64:67]
	v_mfma_f32_16x16x32_bf16 v[64:67], v[170:173], v[202:205], v[64:67]
	s_barrier
	s_add_i32 s20, s55, s56
	v_lshl_add_u64 v[166:167], v[166:167], 0, s[36:37]
	s_mov_b32 m0, s20
	ds_read_b128 v[174:177], v211 offset:49152
	ds_read_b128 v[178:181], v211 offset:50176
	ds_read_b128 v[182:185], v211 offset:51200
	ds_read_b128 v[186:189], v211 offset:52224
	ds_read_b128 v[190:193], v211 offset:53248
	ds_read_b128 v[194:197], v211 offset:54272
	ds_read_b128 v[198:201], v211 offset:55296
	ds_read_b128 v[202:205], v211 offset:56320
	global_load_lds_dwordx4 v[166:167], off
	v_lshl_add_u64 v[166:167], v[212:213], 0, s[36:37]
	s_add_i32 m0, s20, 0x2000
	s_add_i32 s20, s72, s56
	global_load_lds_dwordx4 v[166:167], off
	v_lshl_add_u64 v[166:167], v[214:215], 0, s[36:37]
	s_mov_b32 m0, s20
	s_nop 0
	global_load_lds_dwordx4 v[166:167], off
	v_lshl_add_u64 v[166:167], v[216:217], 0, s[36:37]
	s_add_i32 m0, s20, 0x2000
	s_nop 0
	global_load_lds_dwordx4 v[166:167], off
	v_lshl_add_u64 v[166:167], v[218:219], 0, s[36:37]
	s_mov_b32 m0, s66
	s_nop 0
	global_load_lds_dwordx4 v[166:167], off
	v_lshl_add_u64 v[166:167], v[220:221], 0, s[36:37]
	s_mov_b32 m0, s67
	s_nop 0
	global_load_lds_dwordx4 v[166:167], off
	s_waitcnt vmcnt(8)
	s_waitcnt lgkmcnt(0)
	s_barrier
	v_mfma_f32_16x16x32_bf16 v[60:63], v[88:91], v[174:177], v[60:63]
	v_mfma_f32_16x16x32_bf16 v[60:63], v[100:103], v[178:181], v[60:63]
	v_mfma_f32_16x16x32_bf16 v[56:59], v[112:115], v[174:177], v[56:59]
	v_mfma_f32_16x16x32_bf16 v[56:59], v[124:127], v[178:181], v[56:59]
	v_mfma_f32_16x16x32_bf16 v[44:47], v[88:91], v[182:185], v[44:47]
	v_mfma_f32_16x16x32_bf16 v[44:47], v[100:103], v[186:189], v[44:47]
	v_mfma_f32_16x16x32_bf16 v[40:43], v[112:115], v[182:185], v[40:43]
	v_mfma_f32_16x16x32_bf16 v[40:43], v[124:127], v[186:189], v[40:43]
	v_mfma_f32_16x16x32_bf16 v[28:31], v[88:91], v[190:193], v[28:31]
	v_mfma_f32_16x16x32_bf16 v[28:31], v[100:103], v[194:197], v[28:31]
	v_mfma_f32_16x16x32_bf16 v[24:27], v[112:115], v[190:193], v[24:27]
	v_mfma_f32_16x16x32_bf16 v[24:27], v[124:127], v[194:197], v[24:27]
	v_mfma_f32_16x16x32_bf16 v[12:15], v[88:91], v[198:201], v[12:15]
	v_mfma_f32_16x16x32_bf16 v[12:15], v[100:103], v[202:205], v[12:15]
	v_mfma_f32_16x16x32_bf16 v[8:11], v[112:115], v[198:201], v[8:11]
	v_mfma_f32_16x16x32_bf16 v[8:11], v[124:127], v[202:205], v[8:11]
	v_mfma_f32_16x16x32_bf16 v[52:55], v[136:139], v[174:177], v[52:55]
	v_mfma_f32_16x16x32_bf16 v[52:55], v[148:151], v[178:181], v[52:55]
	v_mfma_f32_16x16x32_bf16 v[48:51], v[152:155], v[174:177], v[48:51]
	v_mfma_f32_16x16x32_bf16 v[48:51], v[170:173], v[178:181], v[48:51]
	v_mfma_f32_16x16x32_bf16 v[36:39], v[136:139], v[182:185], v[36:39]
	v_mfma_f32_16x16x32_bf16 v[36:39], v[148:151], v[186:189], v[36:39]
	v_mfma_f32_16x16x32_bf16 v[32:35], v[152:155], v[182:185], v[32:35]
	v_mfma_f32_16x16x32_bf16 v[32:35], v[170:173], v[186:189], v[32:35]
	v_mfma_f32_16x16x32_bf16 v[20:23], v[136:139], v[190:193], v[20:23]
	v_mfma_f32_16x16x32_bf16 v[20:23], v[148:151], v[194:197], v[20:23]
	v_mfma_f32_16x16x32_bf16 v[16:19], v[152:155], v[190:193], v[16:19]
	v_mfma_f32_16x16x32_bf16 v[16:19], v[170:173], v[194:197], v[16:19]
	v_mfma_f32_16x16x32_bf16 v[4:7], v[136:139], v[198:201], v[4:7]
	v_mfma_f32_16x16x32_bf16 v[4:7], v[148:151], v[202:205], v[4:7]
	v_mfma_f32_16x16x32_bf16 v[0:3], v[152:155], v[198:201], v[0:3]
	v_mfma_f32_16x16x32_bf16 v[0:3], v[170:173], v[202:205], v[0:3]
	s_barrier
	s_add_u32 s44, s44, 0x100
	s_addc_u32 s45, s45, 0
	s_add_u32 s42, s42, 0x100
	s_addc_u32 s43, s43, 0
	s_cmp_ge_u32 s54, s3
	s_mov_b32 s20, s54
	s_cbranch_scc0 .LBB0_575
	s_setprio 0
	s_and_b64 vcc, exec, s[16:17]
	s_cbranch_vccz .LBB0_578
	s_barrier

.LBB0_691:
	s_ashr_i32 s43, s42, 31
	s_lshl_b64 s[44:45], s[42:43], 19
	s_add_u32 s44, s55, s44
	s_addc_u32 s45, s56, s45
	s_and_b64 s[48:49], s[38:39], exec
	s_cselect_b32 s43, s45, s41
	s_cselect_b32 s66, s44, s40
	s_ashr_i32 s19, s18, 31
	s_lshl_b64 s[48:49], s[18:19], 19
	s_add_u32 s48, s52, s48
	s_addc_u32 s49, s53, s49
	s_and_b64 s[50:51], s[38:39], exec
	s_cselect_b32 s19, s49, s21
	s_cselect_b32 s67, s48, s20
	s_add_u32 s68, s20, 0x100
	s_addc_u32 s69, s21, 0
	s_add_u32 s40, s40, 0x40080
	v_mov_b64_e32 v[0:1], 0
	s_addc_u32 s41, s41, 0
	s_mov_b32 s70, -2
	v_mov_b64_e32 v[2:3], 0
	v_mov_b64_e32 v[4:5], 0
	v_mov_b64_e32 v[6:7], 0
	v_mov_b64_e32 v[8:9], 0
	v_mov_b64_e32 v[10:11], 0
	v_mov_b64_e32 v[12:13], 0
	v_mov_b64_e32 v[14:15], 0
	v_mov_b64_e32 v[16:17], 0
	v_mov_b64_e32 v[18:19], 0
	v_mov_b64_e32 v[20:21], 0
	v_mov_b64_e32 v[22:23], 0
	v_mov_b64_e32 v[24:25], 0
	v_mov_b64_e32 v[26:27], 0
	v_mov_b64_e32 v[28:29], 0
	v_mov_b64_e32 v[30:31], 0
	v_mov_b64_e32 v[32:33], 0
	v_mov_b64_e32 v[34:35], 0
	v_mov_b64_e32 v[36:37], 0
	v_mov_b64_e32 v[38:39], 0
	v_mov_b64_e32 v[40:41], 0
	v_mov_b64_e32 v[42:43], 0
	v_mov_b64_e32 v[44:45], 0
	v_mov_b64_e32 v[46:47], 0
	v_mov_b64_e32 v[48:49], 0
	v_mov_b64_e32 v[50:51], 0
	v_mov_b64_e32 v[52:53], 0
	v_mov_b64_e32 v[54:55], 0
	v_mov_b64_e32 v[56:57], 0
	v_mov_b64_e32 v[58:59], 0
	v_mov_b64_e32 v[60:61], 0
	v_mov_b64_e32 v[62:63], 0
	v_mov_b64_e32 v[64:65], 0
	v_mov_b64_e32 v[66:67], 0
	v_mov_b64_e32 v[68:69], 0
	v_mov_b64_e32 v[70:71], 0
	v_mov_b64_e32 v[72:73], 0
	v_mov_b64_e32 v[74:75], 0
	v_mov_b64_e32 v[76:77], 0
	v_mov_b64_e32 v[78:79], 0
	v_mov_b64_e32 v[80:81], 0
	v_mov_b64_e32 v[82:83], 0
	v_mov_b64_e32 v[84:85], 0
	v_mov_b64_e32 v[86:87], 0
	v_mov_b64_e32 v[88:89], 0
	v_mov_b64_e32 v[90:91], 0
	v_mov_b64_e32 v[92:93], 0
	v_mov_b64_e32 v[94:95], 0
	v_mov_b64_e32 v[96:97], 0
	v_mov_b64_e32 v[98:99], 0
	v_mov_b64_e32 v[100:101], 0
	v_mov_b64_e32 v[102:103], 0
	v_mov_b64_e32 v[104:105], 0
	v_mov_b64_e32 v[106:107], 0
	v_mov_b64_e32 v[108:109], 0
	v_mov_b64_e32 v[110:111], 0
	v_mov_b64_e32 v[112:113], 0
	v_mov_b64_e32 v[114:115], 0
	v_mov_b64_e32 v[116:117], 0
	v_mov_b64_e32 v[118:119], 0
	v_mov_b64_e32 v[120:121], 0
	v_mov_b64_e32 v[122:123], 0
	v_mov_b64_e32 v[124:125], 0
	v_mov_b64_e32 v[126:127], 0
	s_cmpk_lt_u32 s81, 0x100
	s_cbranch_scc1 .Lgprio_UP
	s_setprio 1
.Lgprio_UP:
.LBB0_692:
	s_add_u32 s20, s40, 0xfffc0080
	s_addc_u32 s21, s41, -1
	s_add_i32 s71, 0, 0x10000
	s_cmp_eq_u32 s70, 12
	s_cselect_b32 s51, s43, s21
	s_cselect_b32 s50, s66, s20
	s_cselect_b32 s21, s19, s69
	s_cselect_b32 s20, s67, s68
	s_add_i32 s74, 0, 0x14000
	v_add_u32_e32 v150, s71, v156
	v_add_u32_e32 v188, s74, v156
	ds_read_b128 v[138:141], v150
	ds_read_b128 v[142:145], v150 offset:1024
	ds_read_b128 v[146:149], v150 offset:2048
	ds_read_b128 v[150:153], v150 offset:3072
	ds_read_b128 v[176:179], v188
	ds_read_b128 v[180:183], v188 offset:1024
	ds_read_b128 v[184:187], v188 offset:2048
	ds_read_b128 v[188:191], v188 offset:3072
	v_lshl_add_u64 v[224:225], s[40:41], 0, v[136:137]
	s_add_i32 m0, s57, 0xc000
	ds_read_b128 v[192:195], v175
	ds_read_b128 v[196:199], v175 offset:1024
	ds_read_b128 v[200:203], v175 offset:2048
	ds_read_b128 v[204:207], v175 offset:3072
	ds_read_b128 v[208:211], v175 offset:4096
	ds_read_b128 v[212:215], v175 offset:5120
	ds_read_b128 v[216:219], v175 offset:6144
	ds_read_b128 v[220:223], v175 offset:7168
	global_load_lds_dwordx4 v[224:225], off
	v_lshl_add_u64 v[224:225], s[40:41], 0, v[134:135]
	s_add_i32 m0, s57, 0xe000
	s_nop 0
	global_load_lds_dwordx4 v[224:225], off
	s_waitcnt vmcnt(8)
	s_waitcnt lgkmcnt(0)
	s_barrier
	v_mfma_f32_16x16x32_bf16 v[124:127], v[138:141], v[192:195], v[124:127]
	v_mfma_f32_16x16x32_bf16 v[124:127], v[142:145], v[196:199], v[124:127]
	v_mfma_f32_16x16x32_bf16 v[112:115], v[146:149], v[192:195], v[112:115]
	v_mfma_f32_16x16x32_bf16 v[112:115], v[150:153], v[196:199], v[112:115]
	v_mfma_f32_16x16x32_bf16 v[108:111], v[138:141], v[200:203], v[108:111]
	v_mfma_f32_16x16x32_bf16 v[108:111], v[142:145], v[204:207], v[108:111]
	v_mfma_f32_16x16x32_bf16 v[96:99], v[146:149], v[200:203], v[96:99]
	v_mfma_f32_16x16x32_bf16 v[96:99], v[150:153], v[204:207], v[96:99]
	v_mfma_f32_16x16x32_bf16 v[92:95], v[138:141], v[208:211], v[92:95]
	v_mfma_f32_16x16x32_bf16 v[92:95], v[142:145], v[212:215], v[92:95]
	v_mfma_f32_16x16x32_bf16 v[80:83], v[146:149], v[208:211], v[80:83]
	v_mfma_f32_16x16x32_bf16 v[80:83], v[150:153], v[212:215], v[80:83]
	v_mfma_f32_16x16x32_bf16 v[76:79], v[138:141], v[216:219], v[76:79]
	v_mfma_f32_16x16x32_bf16 v[76:79], v[142:145], v[220:223], v[76:79]
	v_mfma_f32_16x16x32_bf16 v[64:67], v[146:149], v[216:219], v[64:67]
	v_mfma_f32_16x16x32_bf16 v[64:67], v[150:153], v[220:223], v[64:67]
	v_mfma_f32_16x16x32_bf16 v[120:123], v[176:179], v[192:195], v[120:123]
	v_mfma_f32_16x16x32_bf16 v[120:123], v[180:183], v[196:199], v[120:123]
	v_mfma_f32_16x16x32_bf16 v[116:119], v[184:187], v[192:195], v[116:119]
	v_mfma_f32_16x16x32_bf16 v[116:119], v[188:191], v[196:199], v[116:119]
	v_mfma_f32_16x16x32_bf16 v[104:107], v[176:179], v[200:203], v[104:107]
	v_mfma_f32_16x16x32_bf16 v[104:107], v[180:183], v[204:207], v[104:107]
	v_mfma_f32_16x16x32_bf16 v[100:103], v[184:187], v[200:203], v[100:103]
	v_mfma_f32_16x16x32_bf16 v[100:103], v[188:191], v[204:207], v[100:103]
	v_mfma_f32_16x16x32_bf16 v[88:91], v[176:179], v[208:211], v[88:91]
	v_mfma_f32_16x16x32_bf16 v[88:91], v[180:183], v[212:215], v[88:91]
	v_mfma_f32_16x16x32_bf16 v[84:87], v[184:187], v[208:211], v[84:87]
	v_mfma_f32_16x16x32_bf16 v[84:87], v[188:191], v[212:215], v[84:87]
	v_mfma_f32_16x16x32_bf16 v[72:75], v[176:179], v[216:219], v[72:75]
	v_mfma_f32_16x16x32_bf16 v[72:75], v[180:183], v[220:223], v[72:75]
	v_mfma_f32_16x16x32_bf16 v[68:71], v[184:187], v[216:219], v[68:71]
	v_mfma_f32_16x16x32_bf16 v[68:71], v[188:191], v[220:223], v[68:71]
	s_barrier
	s_add_i32 s71, s71, s54
	v_lshl_add_u64 v[224:225], s[20:21], 0, v[168:169]
	s_mov_b32 m0, s71
	ds_read_b128 v[192:195], v175 offset:16384
	ds_read_b128 v[196:199], v175 offset:17408
	ds_read_b128 v[200:203], v175 offset:18432
	ds_read_b128 v[204:207], v175 offset:19456
	ds_read_b128 v[208:211], v175 offset:20480
	ds_read_b128 v[212:215], v175 offset:21504
	ds_read_b128 v[216:219], v175 offset:22528
	ds_read_b128 v[220:223], v175 offset:23552
	global_load_lds_dwordx4 v[224:225], off
	s_add_i32 m0, s71, 0x2000
	s_add_u32 s72, s20, 0x40000
	v_lshl_add_u64 v[226:227], s[20:21], 0, v[128:129]
	s_addc_u32 s73, s21, 0
	s_add_i32 s71, s74, s54
	global_load_lds_dwordx4 v[226:227], off
	v_lshl_add_u64 v[228:229], s[72:73], 0, v[168:169]
	s_mov_b32 m0, s71
	v_lshl_add_u64 v[230:231], s[50:51], 0, v[130:131]
	global_load_lds_dwordx4 v[228:229], off
	v_lshl_add_u64 v[228:229], s[72:73], 0, v[128:129]
	s_add_i32 m0, s71, 0x2000
	s_nop 0
	global_load_lds_dwordx4 v[228:229], off
	v_lshl_add_u64 v[228:229], s[50:51], 0, v[132:133]
	s_mov_b32 m0, s57
	s_nop 0
	global_load_lds_dwordx4 v[228:229], off
	s_mov_b32 m0, s58
	s_nop 0
	global_load_lds_dwordx4 v[230:231], off
	s_waitcnt vmcnt(8)
	s_waitcnt lgkmcnt(0)
	s_barrier
	v_mfma_f32_16x16x32_bf16 v[60:63], v[138:141], v[192:195], v[60:63]
	v_mfma_f32_16x16x32_bf16 v[60:63], v[142:145], v[196:199], v[60:63]
	v_mfma_f32_16x16x32_bf16 v[48:51], v[146:149], v[192:195], v[48:51]
	v_mfma_f32_16x16x32_bf16 v[48:51], v[150:153], v[196:199], v[48:51]
	v_mfma_f32_16x16x32_bf16 v[44:47], v[138:141], v[200:203], v[44:47]
	v_mfma_f32_16x16x32_bf16 v[44:47], v[142:145], v[204:207], v[44:47]
	v_mfma_f32_16x16x32_bf16 v[32:35], v[146:149], v[200:203], v[32:35]
	v_mfma_f32_16x16x32_bf16 v[32:35], v[150:153], v[204:207], v[32:35]
	v_mfma_f32_16x16x32_bf16 v[28:31], v[138:141], v[208:211], v[28:31]
	v_mfma_f32_16x16x32_bf16 v[28:31], v[142:145], v[212:215], v[28:31]
	v_mfma_f32_16x16x32_bf16 v[16:19], v[146:149], v[208:211], v[16:19]
	v_mfma_f32_16x16x32_bf16 v[16:19], v[150:153], v[212:215], v[16:19]
	v_mfma_f32_16x16x32_bf16 v[12:15], v[138:141], v[216:219], v[12:15]
	v_mfma_f32_16x16x32_bf16 v[12:15], v[142:145], v[220:223], v[12:15]
	v_mfma_f32_16x16x32_bf16 v[4:7], v[146:149], v[216:219], v[4:7]
	v_mfma_f32_16x16x32_bf16 v[4:7], v[150:153], v[220:223], v[4:7]
	v_mfma_f32_16x16x32_bf16 v[56:59], v[176:179], v[192:195], v[56:59]
	v_mfma_f32_16x16x32_bf16 v[56:59], v[180:183], v[196:199], v[56:59]
	v_mfma_f32_16x16x32_bf16 v[52:55], v[184:187], v[192:195], v[52:55]
	v_mfma_f32_16x16x32_bf16 v[52:55], v[188:191], v[196:199], v[52:55]
	v_mfma_f32_16x16x32_bf16 v[40:43], v[176:179], v[200:203], v[40:43]
	v_mfma_f32_16x16x32_bf16 v[40:43], v[180:183], v[204:207], v[40:43]
	v_mfma_f32_16x16x32_bf16 v[36:39], v[184:187], v[200:203], v[36:39]
	v_mfma_f32_16x16x32_bf16 v[36:39], v[188:191], v[204:207], v[36:39]
	v_mfma_f32_16x16x32_bf16 v[24:27], v[176:179], v[208:211], v[24:27]
	v_mfma_f32_16x16x32_bf16 v[24:27], v[180:183], v[212:215], v[24:27]
	v_mfma_f32_16x16x32_bf16 v[20:23], v[184:187], v[208:211], v[20:23]
	v_mfma_f32_16x16x32_bf16 v[20:23], v[188:191], v[212:215], v[20:23]
	v_mfma_f32_16x16x32_bf16 v[8:11], v[176:179], v[216:219], v[8:11]
	v_mfma_f32_16x16x32_bf16 v[8:11], v[180:183], v[220:223], v[8:11]
	v_mfma_f32_16x16x32_bf16 v[0:3], v[184:187], v[216:219], v[0:3]
	v_mfma_f32_16x16x32_bf16 v[0:3], v[188:191], v[220:223], v[0:3]
	s_barrier
	s_add_i32 s71, 0, 0x18000
	s_add_i32 s72, 0, 0x1c000
	v_add_u32_e32 v150, s71, v156
	v_add_u32_e32 v188, s72, v156
	ds_read_b128 v[138:141], v150
	ds_read_b128 v[142:145], v150 offset:1024
	ds_read_b128 v[146:149], v150 offset:2048
	ds_read_b128 v[150:153], v150 offset:3072
	ds_read_b128 v[176:179], v188
	ds_read_b128 v[180:183], v188 offset:1024
	ds_read_b128 v[184:187], v188 offset:2048
	ds_read_b128 v[188:191], v188 offset:3072
	s_add_u32 s50, s50, 0x40000
	s_addc_u32 s51, s51, 0
	s_mov_b32 m0, s59
	v_lshl_add_u64 v[232:233], s[50:51], 0, v[132:133]
	ds_read_b128 v[192:195], v175 offset:32768
	ds_read_b128 v[196:199], v175 offset:33792
	ds_read_b128 v[200:203], v175 offset:34816
	ds_read_b128 v[204:207], v175 offset:35840
	ds_read_b128 v[208:211], v175 offset:36864
	ds_read_b128 v[212:215], v175 offset:37888
	ds_read_b128 v[216:219], v175 offset:38912
	ds_read_b128 v[220:223], v175 offset:39936
	global_load_lds_dwordx4 v[232:233], off
	v_lshl_add_u64 v[232:233], s[50:51], 0, v[130:131]
	s_mov_b32 m0, s60
	s_nop 0
	global_load_lds_dwordx4 v[232:233], off
	s_waitcnt vmcnt(8)
	s_waitcnt lgkmcnt(0)
	s_barrier
	v_mfma_f32_16x16x32_bf16 v[124:127], v[138:141], v[192:195], v[124:127]
	v_mfma_f32_16x16x32_bf16 v[124:127], v[142:145], v[196:199], v[124:127]
	v_mfma_f32_16x16x32_bf16 v[112:115], v[146:149], v[192:195], v[112:115]
	v_mfma_f32_16x16x32_bf16 v[112:115], v[150:153], v[196:199], v[112:115]
	v_mfma_f32_16x16x32_bf16 v[108:111], v[138:141], v[200:203], v[108:111]
	v_mfma_f32_16x16x32_bf16 v[108:111], v[142:145], v[204:207], v[108:111]
	v_mfma_f32_16x16x32_bf16 v[96:99], v[146:149], v[200:203], v[96:99]
	v_mfma_f32_16x16x32_bf16 v[96:99], v[150:153], v[204:207], v[96:99]
	v_mfma_f32_16x16x32_bf16 v[92:95], v[138:141], v[208:211], v[92:95]
	v_mfma_f32_16x16x32_bf16 v[92:95], v[142:145], v[212:215], v[92:95]
	v_mfma_f32_16x16x32_bf16 v[80:83], v[146:149], v[208:211], v[80:83]
	v_mfma_f32_16x16x32_bf16 v[80:83], v[150:153], v[212:215], v[80:83]
	v_mfma_f32_16x16x32_bf16 v[76:79], v[138:141], v[216:219], v[76:79]
	v_mfma_f32_16x16x32_bf16 v[76:79], v[142:145], v[220:223], v[76:79]
	v_mfma_f32_16x16x32_bf16 v[64:67], v[146:149], v[216:219], v[64:67]
	v_mfma_f32_16x16x32_bf16 v[64:67], v[150:153], v[220:223], v[64:67]
	v_mfma_f32_16x16x32_bf16 v[120:123], v[176:179], v[192:195], v[120:123]
	v_mfma_f32_16x16x32_bf16 v[120:123], v[180:183], v[196:199], v[120:123]
	v_mfma_f32_16x16x32_bf16 v[116:119], v[184:187], v[192:195], v[116:119]
	v_mfma_f32_16x16x32_bf16 v[116:119], v[188:191], v[196:199], v[116:119]
	v_mfma_f32_16x16x32_bf16 v[104:107], v[176:179], v[200:203], v[104:107]
	v_mfma_f32_16x16x32_bf16 v[104:107], v[180:183], v[204:207], v[104:107]
	v_mfma_f32_16x16x32_bf16 v[100:103], v[184:187], v[200:203], v[100:103]
	v_mfma_f32_16x16x32_bf16 v[100:103], v[188:191], v[204:207], v[100:103]
	v_mfma_f32_16x16x32_bf16 v[88:91], v[176:179], v[208:211], v[88:91]
	v_mfma_f32_16x16x32_bf16 v[88:91], v[180:183], v[212:215], v[88:91]
	v_mfma_f32_16x16x32_bf16 v[84:87], v[184:187], v[208:211], v[84:87]
	v_mfma_f32_16x16x32_bf16 v[84:87], v[188:191], v[212:215], v[84:87]
	v_mfma_f32_16x16x32_bf16 v[72:75], v[176:179], v[216:219], v[72:75]
	v_mfma_f32_16x16x32_bf16 v[72:75], v[180:183], v[220:223], v[72:75]
	v_mfma_f32_16x16x32_bf16 v[68:71], v[184:187], v[216:219], v[68:71]
	v_mfma_f32_16x16x32_bf16 v[68:71], v[188:191], v[220:223], v[68:71]
	s_barrier
	s_add_i32 s50, s71, s54
	v_lshl_add_u64 v[224:225], v[224:225], 0, s[36:37]
	s_mov_b32 m0, s50
	ds_read_b128 v[192:195], v175 offset:49152
	ds_read_b128 v[196:199], v175 offset:50176
	ds_read_b128 v[200:203], v175 offset:51200
	ds_read_b128 v[204:207], v175 offset:52224
	ds_read_b128 v[208:211], v175 offset:53248
	ds_read_b128 v[212:215], v175 offset:54272
	ds_read_b128 v[216:219], v175 offset:55296
	ds_read_b128 v[220:223], v175 offset:56320
	global_load_lds_dwordx4 v[224:225], off
	s_add_i32 m0, s50, 0x2000
	s_add_u32 s20, s20, 0x40080
	v_lshl_add_u64 v[224:225], v[226:227], 0, s[36:37]
	s_addc_u32 s21, s21, 0
	s_add_i32 s50, s72, s54
	global_load_lds_dwordx4 v[224:225], off
	v_lshl_add_u64 v[224:225], s[20:21], 0, v[168:169]
	s_mov_b32 m0, s50
	s_nop 0
	global_load_lds_dwordx4 v[224:225], off
	v_lshl_add_u64 v[224:225], s[20:21], 0, v[128:129]
	s_add_i32 m0, s50, 0x2000
	s_nop 0
	global_load_lds_dwordx4 v[224:225], off
	v_lshl_add_u64 v[224:225], v[228:229], 0, s[36:37]
	s_mov_b32 m0, s61
	s_nop 0
	global_load_lds_dwordx4 v[224:225], off
	v_lshl_add_u64 v[224:225], v[230:231], 0, s[36:37]
	s_mov_b32 m0, s62
	s_nop 0
	global_load_lds_dwordx4 v[224:225], off
	s_waitcnt vmcnt(8)
	s_waitcnt lgkmcnt(0)
	s_barrier
	v_mfma_f32_16x16x32_bf16 v[60:63], v[138:141], v[192:195], v[60:63]
	v_mfma_f32_16x16x32_bf16 v[60:63], v[142:145], v[196:199], v[60:63]
	v_mfma_f32_16x16x32_bf16 v[48:51], v[146:149], v[192:195], v[48:51]
	v_mfma_f32_16x16x32_bf16 v[48:51], v[150:153], v[196:199], v[48:51]
	v_mfma_f32_16x16x32_bf16 v[44:47], v[138:141], v[200:203], v[44:47]
	v_mfma_f32_16x16x32_bf16 v[44:47], v[142:145], v[204:207], v[44:47]
	v_mfma_f32_16x16x32_bf16 v[32:35], v[146:149], v[200:203], v[32:35]
	v_mfma_f32_16x16x32_bf16 v[32:35], v[150:153], v[204:207], v[32:35]
	v_mfma_f32_16x16x32_bf16 v[28:31], v[138:141], v[208:211], v[28:31]
	v_mfma_f32_16x16x32_bf16 v[28:31], v[142:145], v[212:215], v[28:31]
	v_mfma_f32_16x16x32_bf16 v[16:19], v[146:149], v[208:211], v[16:19]
	v_mfma_f32_16x16x32_bf16 v[16:19], v[150:153], v[212:215], v[16:19]
	v_mfma_f32_16x16x32_bf16 v[12:15], v[138:141], v[216:219], v[12:15]
	v_mfma_f32_16x16x32_bf16 v[12:15], v[142:145], v[220:223], v[12:15]
	v_mfma_f32_16x16x32_bf16 v[4:7], v[146:149], v[216:219], v[4:7]
	v_mfma_f32_16x16x32_bf16 v[4:7], v[150:153], v[220:223], v[4:7]
	v_mfma_f32_16x16x32_bf16 v[56:59], v[176:179], v[192:195], v[56:59]
	v_mfma_f32_16x16x32_bf16 v[56:59], v[180:183], v[196:199], v[56:59]
	v_mfma_f32_16x16x32_bf16 v[52:55], v[184:187], v[192:195], v[52:55]
	v_mfma_f32_16x16x32_bf16 v[52:55], v[188:191], v[196:199], v[52:55]
	v_mfma_f32_16x16x32_bf16 v[40:43], v[176:179], v[200:203], v[40:43]
	v_mfma_f32_16x16x32_bf16 v[40:43], v[180:183], v[204:207], v[40:43]
	v_mfma_f32_16x16x32_bf16 v[36:39], v[184:187], v[200:203], v[36:39]
	v_mfma_f32_16x16x32_bf16 v[36:39], v[188:191], v[204:207], v[36:39]
	v_mfma_f32_16x16x32_bf16 v[24:27], v[176:179], v[208:211], v[24:27]
	v_mfma_f32_16x16x32_bf16 v[24:27], v[180:183], v[212:215], v[24:27]
	v_mfma_f32_16x16x32_bf16 v[20:23], v[184:187], v[208:211], v[20:23]
	v_mfma_f32_16x16x32_bf16 v[20:23], v[188:191], v[212:215], v[20:23]
	v_mfma_f32_16x16x32_bf16 v[8:11], v[176:179], v[216:219], v[8:11]
	v_mfma_f32_16x16x32_bf16 v[8:11], v[180:183], v[220:223], v[8:11]
	v_mfma_f32_16x16x32_bf16 v[0:3], v[184:187], v[216:219], v[0:3]
	v_mfma_f32_16x16x32_bf16 v[0:3], v[188:191], v[220:223], v[0:3]
	s_barrier
	s_add_i32 s70, s70, 2
	s_add_u32 s68, s68, 0x100
	s_addc_u32 s69, s69, 0
	s_add_u32 s40, s40, 0x100
	s_addc_u32 s41, s41, 0
	s_cmp_gt_u32 s70, 13
	s_cbranch_scc0 .LBB0_692
	s_setprio 0
	s_and_b64 vcc, exec, s[16:17]
	s_cbranch_vccz .LBB0_695
	s_barrier
